# plus GEMM K-loops: LDS-DMA M0 values from SALU adds of per-iteration readfirstlane bases instead of the serial v_add/v_readfirstlane/s_mov chain between pieces
# speedup vs baseline: 1.0282x; 1.0009x over previous
.LBB0_238:
	s_add_i32 s30, s25, 0x8000
	s_and_b32 s31, s30, 0x8000
	v_readfirstlane_b32 s98, v71
	v_readfirstlane_b32 s99, v73
	v_readfirstlane_b32 s100, v74
	v_readfirstlane_b32 s101, v75
	s_waitcnt vmcnt(0)
	s_waitcnt vmcnt(0)
	s_add_u32 m0, s98, s31
	s_barrier
	buffer_load_dwordx4 v70, s[4:7], s24 offen lds
	s_add_u32 m0, s98, s31
	s_add_u32 m0, m0, 0x4000
	s_mov_b32 s10, s6
	s_mov_b32 s11, s7
	buffer_load_dwordx4 v70, s[8:11], s24 offen lds
	s_add_u32 m0, s99, s31
	s_nop 0
	buffer_load_dwordx4 v69, s[4:7], s24 offen lds
	s_add_u32 m0, s99, s31
	s_add_u32 m0, m0, 0x4000
	s_nop 0
	buffer_load_dwordx4 v69, s[8:11], s24 offen lds
	s_add_u32 m0, s100, s31
	s_nop 0
	buffer_load_dwordx4 v68, s[4:7], s24 offen lds
	s_add_u32 m0, s100, s31
	s_add_u32 m0, m0, 0x4000
	s_nop 0
	buffer_load_dwordx4 v68, s[8:11], s24 offen lds
	s_add_u32 m0, s101, s31
	s_nop 0
	buffer_load_dwordx4 v67, s[4:7], s24 offen lds
	s_add_u32 m0, s101, s31
	s_add_u32 m0, m0, 0x4000
	s_nop 0
	buffer_load_dwordx4 v67, s[8:11], s24 offen lds
	s_and_b32 s10, s25, 0x8000
	v_or_b32_e32 v79, s10, v78
	v_add3_u32 v92, v79, s17, v77
	v_add3_u32 v79, v79, s15, v77
	ds_read_b128 v[80:83], v92
	ds_read_b128 v[84:87], v92 offset:2048
	ds_read_b128 v[88:91], v92 offset:4096
	ds_read_b128 v[92:95], v92 offset:6144
	ds_read_b128 v[96:99], v79 offset:16384
	ds_read_b128 v[100:103], v79 offset:18432
	ds_read_b128 v[104:107], v79 offset:20480
	ds_read_b128 v[108:111], v79 offset:22528
	v_or_b32_e32 v79, s10, v76
	v_add3_u32 v124, v79, s17, v77
	v_add3_u32 v79, v79, s15, v77
	ds_read_b128 v[112:115], v124
	ds_read_b128 v[116:119], v124 offset:2048
	ds_read_b128 v[120:123], v124 offset:4096
	ds_read_b128 v[124:127], v124 offset:6144
	ds_read_b128 v[128:131], v79 offset:16384
	ds_read_b128 v[132:135], v79 offset:18432
	ds_read_b128 v[136:139], v79 offset:20480
	ds_read_b128 v[140:143], v79 offset:22528
	s_waitcnt lgkmcnt(11)
	v_mfma_f32_16x16x32_bf16 v[60:63], v[96:99], v[80:83], v[60:63]
	s_waitcnt lgkmcnt(10)
	v_mfma_f32_16x16x32_bf16 v[56:59], v[100:103], v[80:83], v[56:59]
	s_waitcnt lgkmcnt(9)
	v_mfma_f32_16x16x32_bf16 v[52:55], v[104:107], v[80:83], v[52:55]
	s_waitcnt lgkmcnt(8)
	v_mfma_f32_16x16x32_bf16 v[44:47], v[108:111], v[80:83], v[44:47]
	v_mfma_f32_16x16x32_bf16 v[40:43], v[96:99], v[84:87], v[40:43]
	v_mfma_f32_16x16x32_bf16 v[36:39], v[100:103], v[84:87], v[36:39]
	v_mfma_f32_16x16x32_bf16 v[32:35], v[104:107], v[84:87], v[32:35]
	v_mfma_f32_16x16x32_bf16 v[28:31], v[108:111], v[84:87], v[28:31]
	v_mfma_f32_16x16x32_bf16 v[24:27], v[96:99], v[88:91], v[24:27]
	v_mfma_f32_16x16x32_bf16 v[20:23], v[100:103], v[88:91], v[20:23]
	v_mfma_f32_16x16x32_bf16 v[16:19], v[104:107], v[88:91], v[16:19]
	v_mfma_f32_16x16x32_bf16 v[12:15], v[108:111], v[88:91], v[12:15]
	v_mfma_f32_16x16x32_bf16 v[8:11], v[96:99], v[92:95], v[8:11]
	v_mfma_f32_16x16x32_bf16 v[4:7], v[100:103], v[92:95], v[4:7]
	v_mfma_f32_16x16x32_bf16 v[0:3], v[104:107], v[92:95], v[0:3]
	v_mfma_f32_16x16x32_bf16 v[48:51], v[108:111], v[92:95], v[48:51]
	s_waitcnt lgkmcnt(3)
	v_mfma_f32_16x16x32_bf16 v[60:63], v[128:131], v[112:115], v[60:63]
	s_addk_i32 s24, 0x80
	s_cmp_eq_u32 s30, 0x78000
	s_mov_b32 s25, s30
	s_waitcnt lgkmcnt(2)
	v_mfma_f32_16x16x32_bf16 v[56:59], v[132:135], v[112:115], v[56:59]
	s_waitcnt lgkmcnt(1)
	v_mfma_f32_16x16x32_bf16 v[52:55], v[136:139], v[112:115], v[52:55]
	s_waitcnt lgkmcnt(0)
	v_mfma_f32_16x16x32_bf16 v[44:47], v[140:143], v[112:115], v[44:47]
	v_mfma_f32_16x16x32_bf16 v[40:43], v[128:131], v[116:119], v[40:43]
	v_mfma_f32_16x16x32_bf16 v[36:39], v[132:135], v[116:119], v[36:39]
	v_mfma_f32_16x16x32_bf16 v[32:35], v[136:139], v[116:119], v[32:35]
	v_mfma_f32_16x16x32_bf16 v[28:31], v[140:143], v[116:119], v[28:31]
	v_mfma_f32_16x16x32_bf16 v[24:27], v[128:131], v[120:123], v[24:27]
	v_mfma_f32_16x16x32_bf16 v[20:23], v[132:135], v[120:123], v[20:23]
	v_mfma_f32_16x16x32_bf16 v[16:19], v[136:139], v[120:123], v[16:19]
	v_mfma_f32_16x16x32_bf16 v[12:15], v[140:143], v[120:123], v[12:15]
	v_mfma_f32_16x16x32_bf16 v[8:11], v[128:131], v[124:127], v[8:11]
	v_mfma_f32_16x16x32_bf16 v[4:7], v[132:135], v[124:127], v[4:7]
	v_mfma_f32_16x16x32_bf16 v[0:3], v[136:139], v[124:127], v[0:3]
	v_mfma_f32_16x16x32_bf16 v[48:51], v[140:143], v[124:127], v[48:51]
	s_cbranch_scc0 .LBB0_238
	s_waitcnt vmcnt(0)
	s_andn2_b64 vcc, exec, s[18:19]
	s_waitcnt vmcnt(0)
	s_barrier
	s_cbranch_vccnz .LBB0_241
	s_add_u32 s4, s28, s20
	s_addc_u32 s5, s29, s21
	s_add_u32 s8, s36, s22
	v_readfirstlane_b32 s18, v71
	s_addc_u32 s9, s37, s23
	s_and_b32 s5, s5, 0xffff
	s_mov_b32 m0, s18
	v_readfirstlane_b32 s18, v72
	v_add_u32_e32 v81, 0x4000, v73
	s_and_b32 s9, s9, 0xffff
	s_mov_b32 s10, s6
	s_mov_b32 s11, s7
	buffer_load_dwordx4 v70, s[4:7], 0 offen lds
	s_mov_b32 m0, s18
	v_readfirstlane_b32 s18, v73
	buffer_load_dwordx4 v70, s[8:11], 0 offen lds
	s_mov_b32 m0, s18
	v_readfirstlane_b32 s18, v81
	v_add_u32_e32 v80, 0x4000, v74
	buffer_load_dwordx4 v69, s[4:7], 0 offen lds
	s_mov_b32 m0, s18
	v_readfirstlane_b32 s18, v74
	buffer_load_dwordx4 v69, s[8:11], 0 offen lds
	s_mov_b32 m0, s18
	v_readfirstlane_b32 s18, v80
	buffer_load_dwordx4 v68, s[4:7], 0 offen lds
	s_mov_b32 m0, s18
	v_readfirstlane_b32 s18, v75
	v_add_u32_e32 v79, 0x4000, v75
	buffer_load_dwordx4 v68, s[8:11], 0 offen lds
	s_mov_b32 m0, s18
	s_nop 0
	buffer_load_dwordx4 v67, s[4:7], 0 offen lds
	v_readfirstlane_b32 s4, v79
	s_mov_b32 m0, s4
	s_nop 0
	buffer_load_dwordx4 v67, s[8:11], 0 offen lds

.LBB0_1026:
	s_add_i32 s30, s35, 0x8000
	s_and_b32 s31, s30, 0x8000
	v_readfirstlane_b32 s98, v96
	v_readfirstlane_b32 s99, v99
	v_readfirstlane_b32 s100, v100
	v_readfirstlane_b32 s101, v101
	s_waitcnt vmcnt(0)
	s_waitcnt vmcnt(0)
	s_add_u32 m0, s98, s31
	s_barrier
	buffer_load_dwordx4 v104, s[8:11], s34 offen lds
	s_add_u32 m0, s98, s31
	s_add_u32 m0, m0, 0x4000
	s_mov_b32 s14, s10
	s_mov_b32 s15, s11
	buffer_load_dwordx4 v104, s[12:15], s34 offen lds
	s_add_u32 m0, s99, s31
	s_nop 0
	buffer_load_dwordx4 v106, s[8:11], s34 offen lds
	s_add_u32 m0, s99, s31
	s_add_u32 m0, m0, 0x4000
	s_nop 0
	buffer_load_dwordx4 v106, s[12:15], s34 offen lds
	s_add_u32 m0, s100, s31
	s_nop 0
	buffer_load_dwordx4 v108, s[8:11], s34 offen lds
	s_add_u32 m0, s100, s31
	s_add_u32 m0, m0, 0x4000
	s_nop 0
	buffer_load_dwordx4 v108, s[12:15], s34 offen lds
	s_add_u32 m0, s101, s31
	s_nop 0
	buffer_load_dwordx4 v109, s[8:11], s34 offen lds
	s_add_u32 m0, s101, s31
	s_add_u32 m0, m0, 0x4000
	s_nop 0
	buffer_load_dwordx4 v109, s[12:15], s34 offen lds
	s_and_b32 s14, s35, 0x8000
	v_or_b32_e32 v113, s14, v110
	v_add3_u32 v126, v113, s59, v111
	v_add3_u32 v113, v113, s60, v111
	ds_read_b128 v[114:117], v126
	ds_read_b128 v[118:121], v126 offset:2048
	ds_read_b128 v[122:125], v126 offset:4096
	ds_read_b128 v[126:129], v126 offset:6144
	ds_read_b128 v[130:133], v113 offset:16384
	ds_read_b128 v[134:137], v113 offset:18432
	ds_read_b128 v[138:141], v113 offset:20480
	ds_read_b128 v[142:145], v113 offset:22528
	v_or_b32_e32 v113, s14, v112
	v_add3_u32 v158, v113, s59, v111
	v_add3_u32 v113, v113, s60, v111
	ds_read_b128 v[146:149], v158
	ds_read_b128 v[150:153], v158 offset:2048
	ds_read_b128 v[154:157], v158 offset:4096
	ds_read_b128 v[164:167], v158 offset:6144
	ds_read_b128 v[168:171], v113 offset:16384
	ds_read_b128 v[172:175], v113 offset:18432
	ds_read_b128 v[176:179], v113 offset:20480
	ds_read_b128 v[180:183], v113 offset:22528
	s_waitcnt lgkmcnt(11)
	v_mfma_f32_16x16x32_bf16 v[92:95], v[130:133], v[114:117], v[92:95]
	s_waitcnt lgkmcnt(10)
	v_mfma_f32_16x16x32_bf16 v[88:91], v[134:137], v[114:117], v[88:91]
	s_waitcnt lgkmcnt(9)
	v_mfma_f32_16x16x32_bf16 v[84:87], v[138:141], v[114:117], v[84:87]
	s_waitcnt lgkmcnt(8)
	v_mfma_f32_16x16x32_bf16 v[76:79], v[142:145], v[114:117], v[76:79]
	v_mfma_f32_16x16x32_bf16 v[72:75], v[130:133], v[118:121], v[72:75]
	v_mfma_f32_16x16x32_bf16 v[68:71], v[134:137], v[118:121], v[68:71]
	v_mfma_f32_16x16x32_bf16 v[64:67], v[138:141], v[118:121], v[64:67]
	v_mfma_f32_16x16x32_bf16 v[60:63], v[142:145], v[118:121], v[60:63]
	v_mfma_f32_16x16x32_bf16 v[56:59], v[130:133], v[122:125], v[56:59]
	v_mfma_f32_16x16x32_bf16 v[52:55], v[134:137], v[122:125], v[52:55]
	v_mfma_f32_16x16x32_bf16 v[48:51], v[138:141], v[122:125], v[48:51]
	v_mfma_f32_16x16x32_bf16 v[44:47], v[142:145], v[122:125], v[44:47]
	v_mfma_f32_16x16x32_bf16 v[40:43], v[130:133], v[126:129], v[40:43]
	v_mfma_f32_16x16x32_bf16 v[36:39], v[134:137], v[126:129], v[36:39]
	v_mfma_f32_16x16x32_bf16 v[32:35], v[138:141], v[126:129], v[32:35]
	v_mfma_f32_16x16x32_bf16 v[80:83], v[142:145], v[126:129], v[80:83]
	s_waitcnt lgkmcnt(3)
	v_mfma_f32_16x16x32_bf16 v[92:95], v[168:171], v[146:149], v[92:95]
	s_addk_i32 s34, 0x80
	s_cmp_lg_u32 s30, 0x78000
	s_mov_b32 s35, s30
	s_waitcnt lgkmcnt(2)
	v_mfma_f32_16x16x32_bf16 v[88:91], v[172:175], v[146:149], v[88:91]
	s_waitcnt lgkmcnt(1)
	v_mfma_f32_16x16x32_bf16 v[84:87], v[176:179], v[146:149], v[84:87]
	s_waitcnt lgkmcnt(0)
	v_mfma_f32_16x16x32_bf16 v[76:79], v[180:183], v[146:149], v[76:79]
	v_mfma_f32_16x16x32_bf16 v[72:75], v[168:171], v[150:153], v[72:75]
	v_mfma_f32_16x16x32_bf16 v[68:71], v[172:175], v[150:153], v[68:71]
	v_mfma_f32_16x16x32_bf16 v[64:67], v[176:179], v[150:153], v[64:67]
	v_mfma_f32_16x16x32_bf16 v[60:63], v[180:183], v[150:153], v[60:63]
	v_mfma_f32_16x16x32_bf16 v[56:59], v[168:171], v[154:157], v[56:59]
	v_mfma_f32_16x16x32_bf16 v[52:55], v[172:175], v[154:157], v[52:55]
	v_mfma_f32_16x16x32_bf16 v[48:51], v[176:179], v[154:157], v[48:51]
	v_mfma_f32_16x16x32_bf16 v[44:47], v[180:183], v[154:157], v[44:47]
	v_mfma_f32_16x16x32_bf16 v[40:43], v[168:171], v[164:167], v[40:43]
	v_mfma_f32_16x16x32_bf16 v[36:39], v[172:175], v[164:167], v[36:39]
	v_mfma_f32_16x16x32_bf16 v[32:35], v[176:179], v[164:167], v[32:35]
	v_mfma_f32_16x16x32_bf16 v[80:83], v[180:183], v[164:167], v[80:83]
	s_cbranch_scc1 .LBB0_1026
	s_ashr_i32 s8, s57, 31
	s_add_u32 s9, s40, s57
	s_addc_u32 s8, s41, s8
	s_ashr_i32 s12, s56, 31
	s_add_u32 s13, s40, s56
	s_addc_u32 s12, s41, s12
	s_add_u32 s9, s9, s16
	s_addc_u32 s14, s8, s17
	s_add_u32 s8, s9, s18
	s_addc_u32 s9, s14, s19
	s_add_u32 s4, s13, s4
	s_addc_u32 s5, s12, s5
	v_mul_lo_u32 v102, v102, s54
	s_add_u32 s12, s4, s58
	s_addc_u32 s13, s5, 0
	s_and_b32 s9, s9, 0xffff
	v_or_b32_e32 v102, v98, v102
	v_readfirstlane_b32 s16, v96
	v_mul_lo_u32 v103, v103, s54
	v_mul_lo_u32 v104, v105, s54
	v_mul_lo_u32 v105, v107, s54
	s_mov_b32 s4, s8
	s_mov_b32 s5, s9
	v_lshlrev_b32_e32 v102, 1, v102
	s_mov_b32 m0, s16
	v_readfirstlane_b32 s16, v97
	v_or_b32_e32 v103, v98, v103
	v_or_b32_e32 v104, v98, v104
	v_or_b32_e32 v98, v98, v105
	s_and_b32 s13, s13, 0xffff
	s_mov_b32 s14, s6
	s_mov_b32 s15, s7
	v_add_u32_e32 v105, 0x4000, v99
	s_waitcnt vmcnt(0)
	s_waitcnt vmcnt(0)
	s_barrier
	buffer_load_dwordx4 v102, s[4:7], 0 offen lds
	s_mov_b32 m0, s16
	v_readfirstlane_b32 s16, v99
	v_lshlrev_b32_e32 v103, 1, v103
	buffer_load_dwordx4 v102, s[12:15], 0 offen lds
	s_mov_b32 m0, s16
	v_readfirstlane_b32 s16, v105
	v_add_u32_e32 v106, 0x4000, v100
	buffer_load_dwordx4 v103, s[4:7], 0 offen lds
	s_mov_b32 m0, s16
	v_readfirstlane_b32 s16, v100
	v_lshlrev_b32_e32 v104, 1, v104
	buffer_load_dwordx4 v103, s[12:15], 0 offen lds
	s_mov_b32 m0, s16
	v_readfirstlane_b32 s16, v106
	buffer_load_dwordx4 v104, s[4:7], 0 offen lds
	s_mov_b32 m0, s16
	v_readfirstlane_b32 s16, v101
	v_lshlrev_b32_e32 v98, 1, v98
	v_add_u32_e32 v107, 0x4000, v101
	buffer_load_dwordx4 v104, s[12:15], 0 offen lds
	s_mov_b32 m0, s16
	v_add3_u32 v96, v112, s60, v111
	buffer_load_dwordx4 v98, s[4:7], 0 offen lds
	v_readfirstlane_b32 s4, v107
	s_mov_b32 m0, s4
	v_add3_u32 v108, v110, s60, v111
	buffer_load_dwordx4 v98, s[12:15], 0 offen lds
	ds_read_b128 v[100:103], v96 offset:55296
	ds_read_b128 v[104:107], v96 offset:53248
	ds_read_b128 v[114:117], v96 offset:51200
	ds_read_b128 v[118:121], v96 offset:49152
	v_add3_u32 v96, v112, s59, v111
	v_add3_u32 v112, v110, s59, v111
	ds_read_b128 v[122:125], v96 offset:38912
	ds_read_b128 v[126:129], v96 offset:36864
	ds_read_b128 v[130:133], v96 offset:34816
	ds_read_b128 v[134:137], v96 offset:32768
	ds_read_b128 v[96:99], v108 offset:55296
	ds_read_b128 v[138:141], v108 offset:53248
	ds_read_b128 v[142:145], v108 offset:51200
	ds_read_b128 v[146:149], v108 offset:49152
	ds_read_b128 v[108:111], v112 offset:38912
	ds_read_b128 v[150:153], v112 offset:36864
	ds_read_b128 v[154:157], v112 offset:34816
	ds_read_b128 v[164:167], v112 offset:32768
	s_waitcnt lgkmcnt(0)
	v_mfma_f32_16x16x32_bf16 v[88:91], v[142:145], v[164:167], v[88:91]
	v_mfma_f32_16x16x32_bf16 v[84:87], v[138:141], v[164:167], v[84:87]
	v_mfma_f32_16x16x32_bf16 v[76:79], v[96:99], v[164:167], v[76:79]
	v_mfma_f32_16x16x32_bf16 v[72:75], v[146:149], v[154:157], v[72:75]
	v_mfma_f32_16x16x32_bf16 v[68:71], v[142:145], v[154:157], v[68:71]
	v_mfma_f32_16x16x32_bf16 v[64:67], v[138:141], v[154:157], v[64:67]
	v_mfma_f32_16x16x32_bf16 v[60:63], v[96:99], v[154:157], v[60:63]
	v_mfma_f32_16x16x32_bf16 v[56:59], v[146:149], v[150:153], v[56:59]
	v_mfma_f32_16x16x32_bf16 v[52:55], v[142:145], v[150:153], v[52:55]
	v_mfma_f32_16x16x32_bf16 v[48:51], v[138:141], v[150:153], v[48:51]
	v_mfma_f32_16x16x32_bf16 v[44:47], v[96:99], v[150:153], v[44:47]
	v_mfma_f32_16x16x32_bf16 v[40:43], v[146:149], v[108:111], v[40:43]
	v_mfma_f32_16x16x32_bf16 v[36:39], v[142:145], v[108:111], v[36:39]
	v_mfma_f32_16x16x32_bf16 v[32:35], v[138:141], v[108:111], v[32:35]
	v_mfma_f32_16x16x32_bf16 v[92:95], v[146:149], v[164:167], v[92:95]
	v_mfma_f32_16x16x32_bf16 v[108:111], v[96:99], v[108:111], v[80:83]
	v_mfma_f32_16x16x32_bf16 v[96:99], v[118:121], v[134:137], v[92:95]
	s_mov_b64 s[14:15], -1
	s_cmp_eq_u32 s53, 2
	v_mfma_f32_16x16x32_bf16 v[88:91], v[114:117], v[134:137], v[88:91]
	v_mfma_f32_16x16x32_bf16 v[84:87], v[104:107], v[134:137], v[84:87]
	v_mfma_f32_16x16x32_bf16 v[80:83], v[100:103], v[134:137], v[76:79]
	v_mfma_f32_16x16x32_bf16 v[76:79], v[118:121], v[130:133], v[72:75]
	v_mfma_f32_16x16x32_bf16 v[72:75], v[114:117], v[130:133], v[68:71]
	v_mfma_f32_16x16x32_bf16 v[68:71], v[104:107], v[130:133], v[64:67]
	v_mfma_f32_16x16x32_bf16 v[64:67], v[100:103], v[130:133], v[60:63]
	v_mfma_f32_16x16x32_bf16 v[60:63], v[118:121], v[126:129], v[56:59]
	v_mfma_f32_16x16x32_bf16 v[56:59], v[114:117], v[126:129], v[52:55]
	v_mfma_f32_16x16x32_bf16 v[52:55], v[104:107], v[126:129], v[48:51]
	v_mfma_f32_16x16x32_bf16 v[48:51], v[100:103], v[126:129], v[44:47]
	v_mfma_f32_16x16x32_bf16 v[44:47], v[118:121], v[122:125], v[40:43]
	v_mfma_f32_16x16x32_bf16 v[40:43], v[114:117], v[122:125], v[36:39]
	v_mfma_f32_16x16x32_bf16 v[36:39], v[104:107], v[122:125], v[32:35]
	v_mfma_f32_16x16x32_bf16 v[32:35], v[100:103], v[122:125], v[108:111]
	s_cbranch_scc1 .LBB0_1029
	s_mov_b32 s4, 0
	s_ashr_i32 s14, s4, 31
	s_add_u32 s4, s40, s4
	s_mov_b32 s5, 0
	s_addc_u32 s14, s41, s14
	s_ashr_i32 s15, s5, 31
	s_add_u32 s16, s40, s5
	s_addc_u32 s15, s41, s15
	s_add_u32 s4, s4, s28
	s_addc_u32 s5, s14, s29
	s_add_u32 s4, s4, 0x3cb8000
	s_addc_u32 s5, s5, 0
	s_add_i32 s14, s52, s55
	s_add_u32 s14, s16, s14
	s_addc_u32 s15, s15, 0
	s_add_u32 s16, s14, 0x300000
	s_addc_u32 s17, s15, 0
	s_mov_b64 s[14:15], 0

.LBB0_1034:
	s_and_b32 s54, s34, 0x8000
	v_readfirstlane_b32 s98, v166
	s_waitcnt vmcnt(0)
	s_waitcnt vmcnt(0)
	s_add_u32 s99, s98, s54
	s_add_u32 m0, s99, 0x0
	s_barrier
	buffer_load_dwordx4 v171, s[8:11], s35 offen lds
	s_add_u32 m0, s99, 0x4000
	s_mov_b32 s14, s10
	s_mov_b32 s15, s11
	buffer_load_dwordx4 v171, s[12:15], s35 offen lds
	s_add_u32 m0, s99, 0x1000
	s_nop 0
	buffer_load_dwordx4 v172, s[8:11], s35 offen lds
	s_add_u32 m0, s99, 0x5000
	s_nop 0
	buffer_load_dwordx4 v172, s[12:15], s35 offen lds
	s_add_u32 m0, s99, 0x2000
	s_nop 0
	buffer_load_dwordx4 v173, s[8:11], s35 offen lds
	s_add_u32 m0, s99, 0x6000
	s_nop 0
	buffer_load_dwordx4 v173, s[12:15], s35 offen lds
	s_add_u32 m0, s99, 0x3000
	s_nop 0
	buffer_load_dwordx4 v174, s[8:11], s35 offen lds
	s_add_u32 m0, s99, 0x7000
	s_nop 0
	buffer_load_dwordx4 v174, s[12:15], s35 offen lds
	s_add_i32 s14, s34, 0xffff8000
	s_and_b32 s14, s14, 0x8000
	v_or_b32_e32 v175, s14, v164
	v_add3_u32 v188, v175, s56, v160
	v_add3_u32 v175, v175, s55, v160
	ds_read_b128 v[176:179], v188
	ds_read_b128 v[180:183], v188 offset:2048
	ds_read_b128 v[184:187], v188 offset:4096
	ds_read_b128 v[188:191], v188 offset:6144
	ds_read_b128 v[196:199], v175 offset:16384
	ds_read_b128 v[200:203], v175 offset:18432
	ds_read_b128 v[204:207], v175 offset:20480
	ds_read_b128 v[208:211], v175 offset:22528
	v_or_b32_e32 v175, s14, v163
	v_add3_u32 v224, v175, s56, v160
	v_add3_u32 v175, v175, s55, v160
	ds_read_b128 v[212:215], v224
	ds_read_b128 v[216:219], v224 offset:2048
	ds_read_b128 v[220:223], v224 offset:4096
	ds_read_b128 v[224:227], v224 offset:6144
	ds_read_b128 v[228:231], v175 offset:16384
	ds_read_b128 v[232:235], v175 offset:18432
	ds_read_b128 v[236:239], v175 offset:20480
	ds_read_b128 v[240:243], v175 offset:22528
	s_waitcnt lgkmcnt(11)
	v_mfma_f32_16x16x32_bf16 v[156:159], v[196:199], v[176:179], v[156:159]
	s_waitcnt lgkmcnt(10)
	v_mfma_f32_16x16x32_bf16 v[152:155], v[200:203], v[176:179], v[152:155]
	s_waitcnt lgkmcnt(9)
	v_mfma_f32_16x16x32_bf16 v[148:151], v[204:207], v[176:179], v[148:151]
	s_waitcnt lgkmcnt(8)
	v_mfma_f32_16x16x32_bf16 v[140:143], v[208:211], v[176:179], v[140:143]
	v_mfma_f32_16x16x32_bf16 v[136:139], v[196:199], v[180:183], v[136:139]
	v_mfma_f32_16x16x32_bf16 v[132:135], v[200:203], v[180:183], v[132:135]
	v_mfma_f32_16x16x32_bf16 v[128:131], v[204:207], v[180:183], v[128:131]
	v_mfma_f32_16x16x32_bf16 v[124:127], v[208:211], v[180:183], v[124:127]
	v_mfma_f32_16x16x32_bf16 v[120:123], v[196:199], v[184:187], v[120:123]
	v_mfma_f32_16x16x32_bf16 v[116:119], v[200:203], v[184:187], v[116:119]
	v_mfma_f32_16x16x32_bf16 v[112:115], v[204:207], v[184:187], v[112:115]
	v_mfma_f32_16x16x32_bf16 v[108:111], v[208:211], v[184:187], v[108:111]
	v_mfma_f32_16x16x32_bf16 v[104:107], v[196:199], v[188:191], v[104:107]
	v_mfma_f32_16x16x32_bf16 v[100:103], v[200:203], v[188:191], v[100:103]
	v_mfma_f32_16x16x32_bf16 v[92:95], v[204:207], v[188:191], v[92:95]
	v_mfma_f32_16x16x32_bf16 v[144:147], v[208:211], v[188:191], v[144:147]
	s_waitcnt lgkmcnt(3)
	v_mfma_f32_16x16x32_bf16 v[156:159], v[228:231], v[212:215], v[156:159]
	s_add_i32 s34, s34, 0x8000
	s_addk_i32 s35, 0x80
	s_cmp_eq_u32 s19, s34
	s_waitcnt lgkmcnt(2)
	v_mfma_f32_16x16x32_bf16 v[152:155], v[232:235], v[212:215], v[152:155]
	s_waitcnt lgkmcnt(1)
	v_mfma_f32_16x16x32_bf16 v[148:151], v[236:239], v[212:215], v[148:151]
	s_waitcnt lgkmcnt(0)
	v_mfma_f32_16x16x32_bf16 v[140:143], v[240:243], v[212:215], v[140:143]
	v_mfma_f32_16x16x32_bf16 v[136:139], v[228:231], v[216:219], v[136:139]
	v_mfma_f32_16x16x32_bf16 v[132:135], v[232:235], v[216:219], v[132:135]
	v_mfma_f32_16x16x32_bf16 v[128:131], v[236:239], v[216:219], v[128:131]
	v_mfma_f32_16x16x32_bf16 v[124:127], v[240:243], v[216:219], v[124:127]
	v_mfma_f32_16x16x32_bf16 v[120:123], v[228:231], v[220:223], v[120:123]
	v_mfma_f32_16x16x32_bf16 v[116:119], v[232:235], v[220:223], v[116:119]
	v_mfma_f32_16x16x32_bf16 v[112:115], v[236:239], v[220:223], v[112:115]
	v_mfma_f32_16x16x32_bf16 v[108:111], v[240:243], v[220:223], v[108:111]
	v_mfma_f32_16x16x32_bf16 v[104:107], v[228:231], v[224:227], v[104:107]
	v_mfma_f32_16x16x32_bf16 v[100:103], v[232:235], v[224:227], v[100:103]
	v_mfma_f32_16x16x32_bf16 v[92:95], v[236:239], v[224:227], v[92:95]
	v_mfma_f32_16x16x32_bf16 v[144:147], v[240:243], v[224:227], v[144:147]
	s_cbranch_scc0 .LBB0_1034
	s_cmp_eq_u64 s[4:5], 0
	s_waitcnt vmcnt(0)
	s_cselect_b64 s[8:9], -1, 0
	s_and_b64 vcc, exec, s[8:9]
	s_waitcnt vmcnt(0)
	s_barrier
	s_cbranch_vccnz .LBB0_1011
	v_mul_lo_u32 v167, v167, s18
	v_mul_lo_u32 v168, v168, s18
	v_mul_lo_u32 v169, v169, s18
	v_mul_lo_u32 v170, v170, s18
	v_or_b32_e32 v170, v165, v170
	v_or_b32_e32 v169, v165, v169
	v_or_b32_e32 v168, v165, v168
	v_or_b32_e32 v165, v165, v167
	v_add_u32_e32 v176, 0x4000, v166
	v_readfirstlane_b32 s12, v166
	v_add_u32_e32 v173, 0x1000, v166
	s_and_b32 s5, s5, 0xffff
	v_lshlrev_b32_e32 v165, 1, v165
	s_mov_b32 m0, s12
	v_readfirstlane_b32 s12, v176
	v_add_u32_e32 v175, 0x5000, v166
	s_and_b32 s17, s17, 0xffff
	s_mov_b32 s18, s6
	s_mov_b32 s19, s7
	buffer_load_dwordx4 v165, s[4:7], 0 offen lds
	s_mov_b32 m0, s12
	v_readfirstlane_b32 s12, v173
	v_add_u32_e32 v172, 0x2000, v166
	v_lshlrev_b32_e32 v168, 1, v168
	buffer_load_dwordx4 v165, s[16:19], 0 offen lds
	s_mov_b32 m0, s12
	v_readfirstlane_b32 s12, v175
	v_add_u32_e32 v174, 0x6000, v166
	buffer_load_dwordx4 v168, s[4:7], 0 offen lds
	s_mov_b32 m0, s12
	v_readfirstlane_b32 s12, v172
	v_add_u32_e32 v171, 0x3000, v166
	v_lshlrev_b32_e32 v169, 1, v169
	buffer_load_dwordx4 v168, s[16:19], 0 offen lds
	s_mov_b32 m0, s12
	v_readfirstlane_b32 s12, v174
	buffer_load_dwordx4 v169, s[4:7], 0 offen lds
	s_mov_b32 m0, s12
	v_readfirstlane_b32 s12, v171
	v_add_u32_e32 v167, 0x7000, v166
	v_lshlrev_b32_e32 v170, 1, v170
	buffer_load_dwordx4 v169, s[16:19], 0 offen lds
	s_mov_b32 m0, s12
	s_nop 0
	buffer_load_dwordx4 v170, s[4:7], 0 offen lds
	v_readfirstlane_b32 s4, v167
	s_mov_b32 m0, s4
	s_nop 0
	buffer_load_dwordx4 v170, s[16:19], 0 offen lds
	s_branch .LBB0_1011

.LBB0_1100:
	s_add_i32 s30, s35, 0x8000
	s_and_b32 s50, s30, 0x8000
	v_readfirstlane_b32 s98, v68
	v_readfirstlane_b32 s99, v70
	v_readfirstlane_b32 s100, v71
	v_readfirstlane_b32 s101, v72
	s_waitcnt vmcnt(0)
	s_nop 0
	s_add_u32 m0, s98, s50
	s_barrier
	buffer_load_dwordx4 v67, s[8:11], s34 offen lds
	s_add_u32 m0, s98, s50
	s_add_u32 m0, m0, 0x4000
	s_nop 0
	buffer_load_dwordx4 v67, s[12:15], s34 offen lds
	s_add_u32 m0, s99, s50
	s_nop 0
	buffer_load_dwordx4 v66, s[8:11], s34 offen lds
	s_add_u32 m0, s99, s50
	s_add_u32 m0, m0, 0x4000
	s_nop 0
	buffer_load_dwordx4 v66, s[12:15], s34 offen lds
	s_add_u32 m0, s100, s50
	s_nop 0
	buffer_load_dwordx4 v65, s[8:11], s34 offen lds
	s_add_u32 m0, s100, s50
	s_add_u32 m0, m0, 0x4000
	s_nop 0
	buffer_load_dwordx4 v65, s[12:15], s34 offen lds
	s_add_u32 m0, s101, s50
	s_nop 0
	buffer_load_dwordx4 v64, s[8:11], s34 offen lds
	s_add_u32 m0, s101, s50
	s_add_u32 m0, m0, 0x4000
	s_and_b32 s31, s35, 0x8000
	buffer_load_dwordx4 v64, s[12:15], s34 offen lds
	v_or_b32_e32 v92, s31, v75
	v_add3_u32 v88, v92, s49, v73
	v_add3_u32 v92, v92, s25, v73
	ds_read_b128 v[76:79], v88
	ds_read_b128 v[80:83], v88 offset:2048
	ds_read_b128 v[84:87], v88 offset:4096
	ds_read_b128 v[88:91], v88 offset:6144
	ds_read_b128 v[94:97], v92 offset:16384
	ds_read_b128 v[98:101], v92 offset:18432
	ds_read_b128 v[106:109], v92 offset:20480
	ds_read_b128 v[110:113], v92 offset:22528
	v_or_b32_e32 v92, s31, v74
	v_add3_u32 v102, v92, s49, v73
	v_add3_u32 v92, v92, s25, v73
	ds_read_b128 v[114:117], v102
	ds_read_b128 v[118:121], v102 offset:2048
	ds_read_b128 v[122:125], v102 offset:4096
	ds_read_b128 v[126:129], v102 offset:6144
	ds_read_b128 v[130:133], v92 offset:16384
	ds_read_b128 v[134:137], v92 offset:18432
	ds_read_b128 v[138:141], v92 offset:20480
	ds_read_b128 v[142:145], v92 offset:22528
	s_waitcnt lgkmcnt(11)
	v_mfma_f32_16x16x32_bf16 v[60:63], v[94:97], v[76:79], v[60:63]
	s_waitcnt lgkmcnt(10)
	v_mfma_f32_16x16x32_bf16 v[56:59], v[98:101], v[76:79], v[56:59]
	s_waitcnt lgkmcnt(9)
	v_mfma_f32_16x16x32_bf16 v[52:55], v[106:109], v[76:79], v[52:55]
	s_waitcnt lgkmcnt(8)
	v_mfma_f32_16x16x32_bf16 v[48:51], v[110:113], v[76:79], v[48:51]
	v_mfma_f32_16x16x32_bf16 v[44:47], v[94:97], v[80:83], v[44:47]
	v_mfma_f32_16x16x32_bf16 v[36:39], v[98:101], v[80:83], v[36:39]
	v_mfma_f32_16x16x32_bf16 v[32:35], v[106:109], v[80:83], v[32:35]
	v_mfma_f32_16x16x32_bf16 v[28:31], v[110:113], v[80:83], v[28:31]
	v_mfma_f32_16x16x32_bf16 v[24:27], v[94:97], v[84:87], v[24:27]
	v_mfma_f32_16x16x32_bf16 v[20:23], v[98:101], v[84:87], v[20:23]
	v_mfma_f32_16x16x32_bf16 v[16:19], v[106:109], v[84:87], v[16:19]
	v_mfma_f32_16x16x32_bf16 v[12:15], v[110:113], v[84:87], v[12:15]
	v_mfma_f32_16x16x32_bf16 v[8:11], v[94:97], v[88:91], v[8:11]
	v_mfma_f32_16x16x32_bf16 v[4:7], v[98:101], v[88:91], v[4:7]
	v_mfma_f32_16x16x32_bf16 v[0:3], v[106:109], v[88:91], v[0:3]
	v_mfma_f32_16x16x32_bf16 v[40:43], v[110:113], v[88:91], v[40:43]
	s_waitcnt lgkmcnt(3)
	v_mfma_f32_16x16x32_bf16 v[60:63], v[130:133], v[114:117], v[60:63]
	s_addk_i32 s34, 0x80
	s_cmpk_eq_i32 s34, 0x800
	s_mov_b32 s35, s30
	s_waitcnt lgkmcnt(2)
	v_mfma_f32_16x16x32_bf16 v[56:59], v[134:137], v[114:117], v[56:59]
	s_waitcnt lgkmcnt(1)
	v_mfma_f32_16x16x32_bf16 v[52:55], v[138:141], v[114:117], v[52:55]
	s_waitcnt lgkmcnt(0)
	v_mfma_f32_16x16x32_bf16 v[48:51], v[142:145], v[114:117], v[48:51]
	v_mfma_f32_16x16x32_bf16 v[44:47], v[130:133], v[118:121], v[44:47]
	v_mfma_f32_16x16x32_bf16 v[36:39], v[134:137], v[118:121], v[36:39]
	v_mfma_f32_16x16x32_bf16 v[32:35], v[138:141], v[118:121], v[32:35]
	v_mfma_f32_16x16x32_bf16 v[28:31], v[142:145], v[118:121], v[28:31]
	v_mfma_f32_16x16x32_bf16 v[24:27], v[130:133], v[122:125], v[24:27]
	v_mfma_f32_16x16x32_bf16 v[20:23], v[134:137], v[122:125], v[20:23]
	v_mfma_f32_16x16x32_bf16 v[16:19], v[138:141], v[122:125], v[16:19]
	v_mfma_f32_16x16x32_bf16 v[12:15], v[142:145], v[122:125], v[12:15]
	v_mfma_f32_16x16x32_bf16 v[8:11], v[130:133], v[126:129], v[8:11]
	v_mfma_f32_16x16x32_bf16 v[4:7], v[134:137], v[126:129], v[4:7]
	v_mfma_f32_16x16x32_bf16 v[0:3], v[138:141], v[126:129], v[0:3]
	v_mfma_f32_16x16x32_bf16 v[40:43], v[142:145], v[126:129], v[40:43]
	s_cbranch_scc0 .LBB0_1100
	s_waitcnt vmcnt(0)
	s_andn2_b64 vcc, exec, s[26:27]
	s_waitcnt vmcnt(0)
	s_barrier
	s_cbranch_vccnz .LBB0_1103
	s_lshl_b64 s[8:9], s[28:29], 1
	s_add_u32 s8, s16, s8
	s_addc_u32 s9, s46, s9
	s_lshl_b32 s12, s36, 1
	s_add_u32 s12, s47, s12
	v_readfirstlane_b32 s16, v68
	s_addc_u32 s13, s48, 0
	s_and_b32 s9, s9, 0xffff
	s_mov_b32 m0, s16
	v_readfirstlane_b32 s16, v69
	v_add_u32_e32 v78, 0x4000, v70
	s_and_b32 s13, s13, 0xffff
	s_mov_b32 s14, s10
	s_mov_b32 s15, s11
	buffer_load_dwordx4 v67, s[8:11], 0 offen lds
	s_mov_b32 m0, s16
	v_readfirstlane_b32 s16, v70
	buffer_load_dwordx4 v67, s[12:15], 0 offen lds
	s_mov_b32 m0, s16
	v_readfirstlane_b32 s16, v78
	v_add_u32_e32 v77, 0x4000, v71
	buffer_load_dwordx4 v66, s[8:11], 0 offen lds
	s_mov_b32 m0, s16
	v_readfirstlane_b32 s16, v71
	buffer_load_dwordx4 v66, s[12:15], 0 offen lds
	s_mov_b32 m0, s16
	v_readfirstlane_b32 s16, v77
	buffer_load_dwordx4 v65, s[8:11], 0 offen lds
	s_mov_b32 m0, s16
	v_readfirstlane_b32 s16, v72
	v_add_u32_e32 v76, 0x4000, v72
	buffer_load_dwordx4 v65, s[12:15], 0 offen lds
	s_mov_b32 m0, s16
	s_nop 0
	buffer_load_dwordx4 v64, s[8:11], 0 offen lds
	v_readfirstlane_b32 s8, v76
	s_mov_b32 m0, s8
	s_nop 0
	buffer_load_dwordx4 v64, s[12:15], 0 offen lds

.LBB0_1293:
	s_add_i32 s30, s45, 0x8000
	s_and_b32 s31, s30, 0x8000
	v_readfirstlane_b32 s98, v70
	v_readfirstlane_b32 s99, v72
	v_readfirstlane_b32 s100, v73
	v_readfirstlane_b32 s101, v74
	s_waitcnt vmcnt(0)
	s_waitcnt vmcnt(0)
	s_add_u32 m0, s98, s31
	s_barrier
	buffer_load_dwordx4 v69, s[8:11], s44 offen lds
	s_add_u32 m0, s98, s31
	s_add_u32 m0, m0, 0x4000
	s_nop 0
	buffer_load_dwordx4 v69, s[12:15], s44 offen lds
	s_add_u32 m0, s99, s31
	s_nop 0
	buffer_load_dwordx4 v68, s[8:11], s44 offen lds
	s_add_u32 m0, s99, s31
	s_add_u32 m0, m0, 0x4000
	s_nop 0
	buffer_load_dwordx4 v68, s[12:15], s44 offen lds
	s_add_u32 m0, s100, s31
	s_nop 0
	buffer_load_dwordx4 v66, s[8:11], s44 offen lds
	s_add_u32 m0, s100, s31
	s_add_u32 m0, m0, 0x4000
	s_nop 0
	buffer_load_dwordx4 v66, s[12:15], s44 offen lds
	s_add_u32 m0, s101, s31
	s_nop 0
	buffer_load_dwordx4 v64, s[8:11], s44 offen lds
	s_add_u32 m0, s101, s31
	s_add_u32 m0, m0, 0x4000
	s_and_b32 s31, s45, 0x8000
	buffer_load_dwordx4 v64, s[12:15], s44 offen lds
	v_or_b32_e32 v94, s31, v77
	v_or_b32_e32 v126, s31, v75
	v_add3_u32 v90, v94, s39, v76
	v_add3_u32 v106, v94, s21, v76
	v_add3_u32 v122, v126, s39, v76
	v_add3_u32 v138, v126, s21, v76
	ds_read_b128 v[78:81], v90
	ds_read_b128 v[82:85], v90 offset:2048
	ds_read_b128 v[86:89], v90 offset:4096
	ds_read_b128 v[90:93], v90 offset:6144
	ds_read_b128 v[94:97], v106 offset:16384
	ds_read_b128 v[98:101], v106 offset:18432
	ds_read_b128 v[102:105], v106 offset:20480
	ds_read_b128 v[106:109], v106 offset:22528
	ds_read_b128 v[110:113], v122
	ds_read_b128 v[114:117], v122 offset:2048
	ds_read_b128 v[118:121], v122 offset:4096
	ds_read_b128 v[122:125], v122 offset:6144
	ds_read_b128 v[126:129], v138 offset:16384
	ds_read_b128 v[130:133], v138 offset:18432
	ds_read_b128 v[134:137], v138 offset:20480
	ds_read_b128 v[138:141], v138 offset:22528
	s_waitcnt lgkmcnt(11)
	v_mfma_f32_16x16x32_bf16 v[60:63], v[94:97], v[78:81], v[60:63]
	s_waitcnt lgkmcnt(10)
	v_mfma_f32_16x16x32_bf16 v[56:59], v[98:101], v[78:81], v[56:59]
	s_waitcnt lgkmcnt(9)
	v_mfma_f32_16x16x32_bf16 v[52:55], v[102:105], v[78:81], v[52:55]
	s_waitcnt lgkmcnt(8)
	v_mfma_f32_16x16x32_bf16 v[48:51], v[106:109], v[78:81], v[48:51]
	v_mfma_f32_16x16x32_bf16 v[40:43], v[94:97], v[82:85], v[40:43]
	v_mfma_f32_16x16x32_bf16 v[36:39], v[98:101], v[82:85], v[36:39]
	v_mfma_f32_16x16x32_bf16 v[32:35], v[102:105], v[82:85], v[32:35]
	v_mfma_f32_16x16x32_bf16 v[28:31], v[106:109], v[82:85], v[28:31]
	v_mfma_f32_16x16x32_bf16 v[24:27], v[94:97], v[86:89], v[24:27]
	v_mfma_f32_16x16x32_bf16 v[20:23], v[98:101], v[86:89], v[20:23]
	v_mfma_f32_16x16x32_bf16 v[16:19], v[102:105], v[86:89], v[16:19]
	v_mfma_f32_16x16x32_bf16 v[12:15], v[106:109], v[86:89], v[12:15]
	v_mfma_f32_16x16x32_bf16 v[8:11], v[94:97], v[90:93], v[8:11]
	v_mfma_f32_16x16x32_bf16 v[4:7], v[98:101], v[90:93], v[4:7]
	v_mfma_f32_16x16x32_bf16 v[0:3], v[102:105], v[90:93], v[0:3]
	v_mfma_f32_16x16x32_bf16 v[44:47], v[106:109], v[90:93], v[44:47]
	s_waitcnt lgkmcnt(3)
	v_mfma_f32_16x16x32_bf16 v[60:63], v[126:129], v[110:113], v[60:63]
	s_addk_i32 s44, 0x80
	s_cmp_eq_u32 s30, 0x78000
	s_mov_b32 s45, s30
	s_waitcnt lgkmcnt(2)
	v_mfma_f32_16x16x32_bf16 v[56:59], v[130:133], v[110:113], v[56:59]
	s_waitcnt lgkmcnt(1)
	v_mfma_f32_16x16x32_bf16 v[52:55], v[134:137], v[110:113], v[52:55]
	s_waitcnt lgkmcnt(0)
	v_mfma_f32_16x16x32_bf16 v[48:51], v[138:141], v[110:113], v[48:51]
	v_mfma_f32_16x16x32_bf16 v[40:43], v[126:129], v[114:117], v[40:43]
	v_mfma_f32_16x16x32_bf16 v[36:39], v[130:133], v[114:117], v[36:39]
	v_mfma_f32_16x16x32_bf16 v[32:35], v[134:137], v[114:117], v[32:35]
	v_mfma_f32_16x16x32_bf16 v[28:31], v[138:141], v[114:117], v[28:31]
	v_mfma_f32_16x16x32_bf16 v[24:27], v[126:129], v[118:121], v[24:27]
	v_mfma_f32_16x16x32_bf16 v[20:23], v[130:133], v[118:121], v[20:23]
	v_mfma_f32_16x16x32_bf16 v[16:19], v[134:137], v[118:121], v[16:19]
	v_mfma_f32_16x16x32_bf16 v[12:15], v[138:141], v[118:121], v[12:15]
	v_mfma_f32_16x16x32_bf16 v[8:11], v[126:129], v[122:125], v[8:11]
	v_mfma_f32_16x16x32_bf16 v[4:7], v[130:133], v[122:125], v[4:7]
	v_mfma_f32_16x16x32_bf16 v[0:3], v[134:137], v[122:125], v[0:3]
	v_mfma_f32_16x16x32_bf16 v[44:47], v[138:141], v[122:125], v[44:47]
	s_cbranch_scc0 .LBB0_1293
	s_waitcnt vmcnt(0)
	s_andn2_b64 vcc, exec, s[22:23]
	s_waitcnt vmcnt(0)
	s_barrier
	s_cbranch_vccnz .LBB0_1284
	s_add_u32 s8, s35, s24
	s_addc_u32 s9, s36, s25
	s_add_u32 s12, s37, s26
	v_readfirstlane_b32 s22, v70
	s_addc_u32 s13, s38, s27
	s_and_b32 s9, s9, 0xffff
	s_mov_b32 m0, s22
	v_readfirstlane_b32 s22, v71
	v_add_u32_e32 v80, 0x4000, v72
	s_and_b32 s13, s13, 0xffff
	s_mov_b32 s14, s10
	s_mov_b32 s15, s11
	buffer_load_dwordx4 v69, s[8:11], 0 offen lds
	s_mov_b32 m0, s22
	v_readfirstlane_b32 s22, v72
	buffer_load_dwordx4 v69, s[12:15], 0 offen lds
	s_mov_b32 m0, s22
	v_readfirstlane_b32 s22, v80
	v_add_u32_e32 v79, 0x4000, v73
	buffer_load_dwordx4 v68, s[8:11], 0 offen lds
	s_mov_b32 m0, s22
	v_readfirstlane_b32 s22, v73
	buffer_load_dwordx4 v68, s[12:15], 0 offen lds
	s_mov_b32 m0, s22
	v_readfirstlane_b32 s22, v79
	buffer_load_dwordx4 v66, s[8:11], 0 offen lds
	s_mov_b32 m0, s22
	v_readfirstlane_b32 s22, v74
	v_add_u32_e32 v78, 0x4000, v74
	buffer_load_dwordx4 v66, s[12:15], 0 offen lds
	s_mov_b32 m0, s22
	s_nop 0
	buffer_load_dwordx4 v64, s[8:11], 0 offen lds
	v_readfirstlane_b32 s8, v78
	s_mov_b32 m0, s8
	s_nop 0
	buffer_load_dwordx4 v64, s[12:15], 0 offen lds
	s_branch .LBB0_1284

.LBB0_1360:
	s_add_i32 s30, s51, 0x8000
	s_and_b32 s52, s30, 0x8000
	v_readfirstlane_b32 s98, v68
	v_readfirstlane_b32 s99, v70
	v_readfirstlane_b32 s100, v71
	v_readfirstlane_b32 s101, v72
	s_waitcnt vmcnt(0)
	s_nop 0
	s_add_u32 m0, s98, s52
	s_barrier
	buffer_load_dwordx4 v67, s[12:15], s50 offen lds
	s_add_u32 m0, s98, s52
	s_add_u32 m0, m0, 0x4000
	s_nop 0
	buffer_load_dwordx4 v67, s[16:19], s50 offen lds
	s_add_u32 m0, s99, s52
	s_nop 0
	buffer_load_dwordx4 v66, s[12:15], s50 offen lds
	s_add_u32 m0, s99, s52
	s_add_u32 m0, m0, 0x4000
	s_nop 0
	buffer_load_dwordx4 v66, s[16:19], s50 offen lds
	s_add_u32 m0, s100, s52
	s_nop 0
	buffer_load_dwordx4 v65, s[12:15], s50 offen lds
	s_add_u32 m0, s100, s52
	s_add_u32 m0, m0, 0x4000
	s_nop 0
	buffer_load_dwordx4 v65, s[16:19], s50 offen lds
	s_add_u32 m0, s101, s52
	s_nop 0
	buffer_load_dwordx4 v64, s[12:15], s50 offen lds
	s_add_u32 m0, s101, s52
	s_add_u32 m0, m0, 0x4000
	s_and_b32 s31, s51, 0x8000
	buffer_load_dwordx4 v64, s[16:19], s50 offen lds
	v_or_b32_e32 v80, s31, v75
	v_add3_u32 v83, v80, s49, v73
	v_add3_u32 v80, v80, s27, v73
	ds_read_b128 v[76:79], v83
	ds_read_b128 v[84:87], v83 offset:2048
	ds_read_b128 v[88:91], v83 offset:4096
	ds_read_b128 v[92:95], v83 offset:6144
	ds_read_b128 v[96:99], v80 offset:16384
	ds_read_b128 v[100:103], v80 offset:18432
	ds_read_b128 v[104:107], v80 offset:20480
	ds_read_b128 v[108:111], v80 offset:22528
	v_or_b32_e32 v80, s31, v74
	v_add3_u32 v83, v80, s49, v73
	v_add3_u32 v80, v80, s27, v73
	ds_read_b128 v[112:115], v83
	ds_read_b128 v[116:119], v83 offset:2048
	ds_read_b128 v[120:123], v83 offset:4096
	ds_read_b128 v[124:127], v83 offset:6144
	ds_read_b128 v[128:131], v80 offset:16384
	ds_read_b128 v[132:135], v80 offset:18432
	ds_read_b128 v[136:139], v80 offset:20480
	ds_read_b128 v[140:143], v80 offset:22528
	s_waitcnt lgkmcnt(11)
	v_mfma_f32_16x16x32_bf16 v[60:63], v[96:99], v[76:79], v[60:63]
	s_waitcnt lgkmcnt(10)
	v_mfma_f32_16x16x32_bf16 v[56:59], v[100:103], v[76:79], v[56:59]
	s_waitcnt lgkmcnt(9)
	v_mfma_f32_16x16x32_bf16 v[52:55], v[104:107], v[76:79], v[52:55]
	s_waitcnt lgkmcnt(8)
	v_mfma_f32_16x16x32_bf16 v[48:51], v[108:111], v[76:79], v[48:51]
	v_mfma_f32_16x16x32_bf16 v[44:47], v[96:99], v[84:87], v[44:47]
	v_mfma_f32_16x16x32_bf16 v[36:39], v[100:103], v[84:87], v[36:39]
	v_mfma_f32_16x16x32_bf16 v[32:35], v[104:107], v[84:87], v[32:35]
	v_mfma_f32_16x16x32_bf16 v[28:31], v[108:111], v[84:87], v[28:31]
	v_mfma_f32_16x16x32_bf16 v[24:27], v[96:99], v[88:91], v[24:27]
	v_mfma_f32_16x16x32_bf16 v[20:23], v[100:103], v[88:91], v[20:23]
	v_mfma_f32_16x16x32_bf16 v[16:19], v[104:107], v[88:91], v[16:19]
	v_mfma_f32_16x16x32_bf16 v[12:15], v[108:111], v[88:91], v[12:15]
	v_mfma_f32_16x16x32_bf16 v[8:11], v[96:99], v[92:95], v[8:11]
	v_mfma_f32_16x16x32_bf16 v[4:7], v[100:103], v[92:95], v[4:7]
	v_mfma_f32_16x16x32_bf16 v[0:3], v[104:107], v[92:95], v[0:3]
	v_mfma_f32_16x16x32_bf16 v[40:43], v[108:111], v[92:95], v[40:43]
	s_waitcnt lgkmcnt(3)
	v_mfma_f32_16x16x32_bf16 v[60:63], v[128:131], v[112:115], v[60:63]
	s_addk_i32 s50, 0x80
	s_cmpk_eq_i32 s50, 0x2000
	s_mov_b32 s51, s30
	s_waitcnt lgkmcnt(2)
	v_mfma_f32_16x16x32_bf16 v[56:59], v[132:135], v[112:115], v[56:59]
	s_waitcnt lgkmcnt(1)
	v_mfma_f32_16x16x32_bf16 v[52:55], v[136:139], v[112:115], v[52:55]
	s_waitcnt lgkmcnt(0)
	v_mfma_f32_16x16x32_bf16 v[48:51], v[140:143], v[112:115], v[48:51]
	v_mfma_f32_16x16x32_bf16 v[44:47], v[128:131], v[116:119], v[44:47]
	v_mfma_f32_16x16x32_bf16 v[36:39], v[132:135], v[116:119], v[36:39]
	v_mfma_f32_16x16x32_bf16 v[32:35], v[136:139], v[116:119], v[32:35]
	v_mfma_f32_16x16x32_bf16 v[28:31], v[140:143], v[116:119], v[28:31]
	v_mfma_f32_16x16x32_bf16 v[24:27], v[128:131], v[120:123], v[24:27]
	v_mfma_f32_16x16x32_bf16 v[20:23], v[132:135], v[120:123], v[20:23]
	v_mfma_f32_16x16x32_bf16 v[16:19], v[136:139], v[120:123], v[16:19]
	v_mfma_f32_16x16x32_bf16 v[12:15], v[140:143], v[120:123], v[12:15]
	v_mfma_f32_16x16x32_bf16 v[8:11], v[128:131], v[124:127], v[8:11]
	v_mfma_f32_16x16x32_bf16 v[4:7], v[132:135], v[124:127], v[4:7]
	v_mfma_f32_16x16x32_bf16 v[0:3], v[136:139], v[124:127], v[0:3]
	v_mfma_f32_16x16x32_bf16 v[40:43], v[140:143], v[124:127], v[40:43]
	s_cbranch_scc0 .LBB0_1360
	s_waitcnt vmcnt(0)
	s_andn2_b64 vcc, exec, s[28:29]
	s_waitcnt vmcnt(0)
	s_barrier
	s_cbranch_vccnz .LBB0_1363
	s_lshl_b64 s[12:13], s[34:35], 1
	s_add_u32 s12, s45, s12
	s_addc_u32 s13, s46, s13
	s_lshl_b32 s16, s36, 1
	s_add_u32 s16, s47, s16
	v_readfirstlane_b32 s28, v68
	s_addc_u32 s17, s48, 0
	s_and_b32 s13, s13, 0xffff
	s_mov_b32 m0, s28
	v_readfirstlane_b32 s28, v69
	v_add_u32_e32 v78, 0x4000, v70
	s_and_b32 s17, s17, 0xffff
	s_mov_b32 s18, s14
	s_mov_b32 s19, s15
	buffer_load_dwordx4 v67, s[12:15], 0 offen lds
	s_mov_b32 m0, s28
	v_readfirstlane_b32 s28, v70
	buffer_load_dwordx4 v67, s[16:19], 0 offen lds
	s_mov_b32 m0, s28
	v_readfirstlane_b32 s28, v78
	v_add_u32_e32 v77, 0x4000, v71
	buffer_load_dwordx4 v66, s[12:15], 0 offen lds
	s_mov_b32 m0, s28
	v_readfirstlane_b32 s28, v71
	buffer_load_dwordx4 v66, s[16:19], 0 offen lds
	s_mov_b32 m0, s28
	v_readfirstlane_b32 s28, v77
	buffer_load_dwordx4 v65, s[12:15], 0 offen lds
	s_mov_b32 m0, s28
	v_readfirstlane_b32 s28, v72
	v_add_u32_e32 v76, 0x4000, v72
	buffer_load_dwordx4 v65, s[16:19], 0 offen lds
	s_mov_b32 m0, s28
	s_nop 0
	buffer_load_dwordx4 v64, s[12:15], 0 offen lds
	v_readfirstlane_b32 s12, v76
	s_mov_b32 m0, s12
	s_nop 0
	buffer_load_dwordx4 v64, s[16:19], 0 offen lds

.LBB0_1496:
	s_add_i32 s30, s27, 0x8000
	s_and_b32 s31, s30, 0x8000
	v_readfirstlane_b32 s98, v71
	v_readfirstlane_b32 s99, v73
	v_readfirstlane_b32 s100, v74
	v_readfirstlane_b32 s101, v75
	s_waitcnt vmcnt(0)
	s_waitcnt vmcnt(0)
	s_add_u32 m0, s98, s31
	s_barrier
	buffer_load_dwordx4 v70, s[8:11], s26 offen lds
	s_add_u32 m0, s98, s31
	s_add_u32 m0, m0, 0x4000
	s_mov_b32 s14, s10
	s_mov_b32 s15, s11
	buffer_load_dwordx4 v70, s[12:15], s26 offen lds
	s_add_u32 m0, s99, s31
	s_nop 0
	buffer_load_dwordx4 v69, s[8:11], s26 offen lds
	s_add_u32 m0, s99, s31
	s_add_u32 m0, m0, 0x4000
	s_nop 0
	buffer_load_dwordx4 v69, s[12:15], s26 offen lds
	s_add_u32 m0, s100, s31
	s_nop 0
	buffer_load_dwordx4 v68, s[8:11], s26 offen lds
	s_add_u32 m0, s100, s31
	s_add_u32 m0, m0, 0x4000
	s_nop 0
	buffer_load_dwordx4 v68, s[12:15], s26 offen lds
	s_add_u32 m0, s101, s31
	s_nop 0
	buffer_load_dwordx4 v67, s[8:11], s26 offen lds
	s_add_u32 m0, s101, s31
	s_add_u32 m0, m0, 0x4000
	s_nop 0
	buffer_load_dwordx4 v67, s[12:15], s26 offen lds
	s_and_b32 s14, s27, 0x8000
	v_or_b32_e32 v79, s14, v78
	v_add3_u32 v92, v79, s19, v77
	v_add3_u32 v79, v79, s17, v77
	ds_read_b128 v[80:83], v92
	ds_read_b128 v[84:87], v92 offset:2048
	ds_read_b128 v[88:91], v92 offset:4096
	ds_read_b128 v[92:95], v92 offset:6144
	ds_read_b128 v[96:99], v79 offset:16384
	ds_read_b128 v[100:103], v79 offset:18432
	ds_read_b128 v[104:107], v79 offset:20480
	ds_read_b128 v[108:111], v79 offset:22528
	v_or_b32_e32 v79, s14, v76
	v_add3_u32 v124, v79, s19, v77
	v_add3_u32 v79, v79, s17, v77
	ds_read_b128 v[112:115], v124
	ds_read_b128 v[116:119], v124 offset:2048
	ds_read_b128 v[120:123], v124 offset:4096
	ds_read_b128 v[124:127], v124 offset:6144
	ds_read_b128 v[128:131], v79 offset:16384
	ds_read_b128 v[132:135], v79 offset:18432
	ds_read_b128 v[136:139], v79 offset:20480
	ds_read_b128 v[140:143], v79 offset:22528
	s_waitcnt lgkmcnt(11)
	v_mfma_f32_16x16x32_bf16 v[60:63], v[96:99], v[80:83], v[60:63]
	s_waitcnt lgkmcnt(10)
	v_mfma_f32_16x16x32_bf16 v[56:59], v[100:103], v[80:83], v[56:59]
	s_waitcnt lgkmcnt(9)
	v_mfma_f32_16x16x32_bf16 v[52:55], v[104:107], v[80:83], v[52:55]
	s_waitcnt lgkmcnt(8)
	v_mfma_f32_16x16x32_bf16 v[44:47], v[108:111], v[80:83], v[44:47]
	v_mfma_f32_16x16x32_bf16 v[40:43], v[96:99], v[84:87], v[40:43]
	v_mfma_f32_16x16x32_bf16 v[36:39], v[100:103], v[84:87], v[36:39]
	v_mfma_f32_16x16x32_bf16 v[32:35], v[104:107], v[84:87], v[32:35]
	v_mfma_f32_16x16x32_bf16 v[28:31], v[108:111], v[84:87], v[28:31]
	v_mfma_f32_16x16x32_bf16 v[24:27], v[96:99], v[88:91], v[24:27]
	v_mfma_f32_16x16x32_bf16 v[20:23], v[100:103], v[88:91], v[20:23]
	v_mfma_f32_16x16x32_bf16 v[16:19], v[104:107], v[88:91], v[16:19]
	v_mfma_f32_16x16x32_bf16 v[12:15], v[108:111], v[88:91], v[12:15]
	v_mfma_f32_16x16x32_bf16 v[8:11], v[96:99], v[92:95], v[8:11]
	v_mfma_f32_16x16x32_bf16 v[4:7], v[100:103], v[92:95], v[4:7]
	v_mfma_f32_16x16x32_bf16 v[0:3], v[104:107], v[92:95], v[0:3]
	v_mfma_f32_16x16x32_bf16 v[48:51], v[108:111], v[92:95], v[48:51]
	s_waitcnt lgkmcnt(3)
	v_mfma_f32_16x16x32_bf16 v[60:63], v[128:131], v[112:115], v[60:63]
	s_addk_i32 s26, 0x80
	s_cmp_eq_u32 s30, 0x78000
	s_mov_b32 s27, s30
	s_waitcnt lgkmcnt(2)
	v_mfma_f32_16x16x32_bf16 v[56:59], v[132:135], v[112:115], v[56:59]
	s_waitcnt lgkmcnt(1)
	v_mfma_f32_16x16x32_bf16 v[52:55], v[136:139], v[112:115], v[52:55]
	s_waitcnt lgkmcnt(0)
	v_mfma_f32_16x16x32_bf16 v[44:47], v[140:143], v[112:115], v[44:47]
	v_mfma_f32_16x16x32_bf16 v[40:43], v[128:131], v[116:119], v[40:43]
	v_mfma_f32_16x16x32_bf16 v[36:39], v[132:135], v[116:119], v[36:39]
	v_mfma_f32_16x16x32_bf16 v[32:35], v[136:139], v[116:119], v[32:35]
	v_mfma_f32_16x16x32_bf16 v[28:31], v[140:143], v[116:119], v[28:31]
	v_mfma_f32_16x16x32_bf16 v[24:27], v[128:131], v[120:123], v[24:27]
	v_mfma_f32_16x16x32_bf16 v[20:23], v[132:135], v[120:123], v[20:23]
	v_mfma_f32_16x16x32_bf16 v[16:19], v[136:139], v[120:123], v[16:19]
	v_mfma_f32_16x16x32_bf16 v[12:15], v[140:143], v[120:123], v[12:15]
	v_mfma_f32_16x16x32_bf16 v[8:11], v[128:131], v[124:127], v[8:11]
	v_mfma_f32_16x16x32_bf16 v[4:7], v[132:135], v[124:127], v[4:7]
	v_mfma_f32_16x16x32_bf16 v[0:3], v[136:139], v[124:127], v[0:3]
	v_mfma_f32_16x16x32_bf16 v[48:51], v[140:143], v[124:127], v[48:51]
	s_cbranch_scc0 .LBB0_1496
	s_waitcnt vmcnt(0)
	s_andn2_b64 vcc, exec, s[20:21]
	s_waitcnt vmcnt(0)
	s_barrier
	s_cbranch_vccnz .LBB0_1499
	s_add_u32 s8, s34, s22
	s_addc_u32 s9, s35, s23
	s_add_u32 s12, s36, s24
	v_readfirstlane_b32 s20, v71
	s_addc_u32 s13, s37, s25
	s_and_b32 s9, s9, 0xffff
	s_mov_b32 m0, s20
	v_readfirstlane_b32 s20, v72
	v_add_u32_e32 v81, 0x4000, v73
	s_and_b32 s13, s13, 0xffff
	s_mov_b32 s14, s10
	s_mov_b32 s15, s11
	buffer_load_dwordx4 v70, s[8:11], 0 offen lds
	s_mov_b32 m0, s20
	v_readfirstlane_b32 s20, v73
	buffer_load_dwordx4 v70, s[12:15], 0 offen lds
	s_mov_b32 m0, s20
	v_readfirstlane_b32 s20, v81
	v_add_u32_e32 v80, 0x4000, v74
	buffer_load_dwordx4 v69, s[8:11], 0 offen lds
	s_mov_b32 m0, s20
	v_readfirstlane_b32 s20, v74
	buffer_load_dwordx4 v69, s[12:15], 0 offen lds
	s_mov_b32 m0, s20
	v_readfirstlane_b32 s20, v80
	buffer_load_dwordx4 v68, s[8:11], 0 offen lds
	s_mov_b32 m0, s20
	v_readfirstlane_b32 s20, v75
	v_add_u32_e32 v79, 0x4000, v75
	buffer_load_dwordx4 v68, s[12:15], 0 offen lds
	s_mov_b32 m0, s20
	s_nop 0
	buffer_load_dwordx4 v67, s[8:11], 0 offen lds
	v_readfirstlane_b32 s8, v79
	s_mov_b32 m0, s8
	s_nop 0
	buffer_load_dwordx4 v67, s[12:15], 0 offen lds

.LBB0_2236:
	s_add_i32 s30, s62, 0x8000
	s_and_b32 s31, s30, 0x8000
	v_readfirstlane_b32 s98, v96
	v_readfirstlane_b32 s99, v99
	v_readfirstlane_b32 s100, v100
	v_readfirstlane_b32 s101, v101
	s_waitcnt vmcnt(0)
	s_waitcnt vmcnt(0)
	s_add_u32 m0, s98, s31
	s_barrier
	buffer_load_dwordx4 v104, s[12:15], s61 offen lds
	s_add_u32 m0, s98, s31
	s_add_u32 m0, m0, 0x4000
	s_mov_b32 s18, s14
	s_mov_b32 s19, s15
	buffer_load_dwordx4 v104, s[16:19], s61 offen lds
	s_add_u32 m0, s99, s31
	s_nop 0
	buffer_load_dwordx4 v106, s[12:15], s61 offen lds
	s_add_u32 m0, s99, s31
	s_add_u32 m0, m0, 0x4000
	s_nop 0
	buffer_load_dwordx4 v106, s[16:19], s61 offen lds
	s_add_u32 m0, s100, s31
	s_nop 0
	buffer_load_dwordx4 v108, s[12:15], s61 offen lds
	s_add_u32 m0, s100, s31
	s_add_u32 m0, m0, 0x4000
	s_nop 0
	buffer_load_dwordx4 v108, s[16:19], s61 offen lds
	s_add_u32 m0, s101, s31
	s_nop 0
	buffer_load_dwordx4 v110, s[12:15], s61 offen lds
	s_add_u32 m0, s101, s31
	s_add_u32 m0, m0, 0x4000
	s_nop 0
	buffer_load_dwordx4 v110, s[16:19], s61 offen lds
	s_and_b32 s18, s62, 0x8000
	v_or_b32_e32 v113, s18, v109
	v_add3_u32 v126, v113, s59, v111
	v_add3_u32 v113, v113, s60, v111
	ds_read_b128 v[114:117], v126
	ds_read_b128 v[118:121], v126 offset:2048
	ds_read_b128 v[122:125], v126 offset:4096
	ds_read_b128 v[126:129], v126 offset:6144
	ds_read_b128 v[130:133], v113 offset:16384
	ds_read_b128 v[134:137], v113 offset:18432
	ds_read_b128 v[138:141], v113 offset:20480
	ds_read_b128 v[142:145], v113 offset:22528
	v_or_b32_e32 v113, s18, v112
	v_add3_u32 v158, v113, s59, v111
	v_add3_u32 v113, v113, s60, v111
	ds_read_b128 v[146:149], v158
	ds_read_b128 v[150:153], v158 offset:2048
	ds_read_b128 v[154:157], v158 offset:4096
	ds_read_b128 v[164:167], v158 offset:6144
	ds_read_b128 v[168:171], v113 offset:16384
	ds_read_b128 v[172:175], v113 offset:18432
	ds_read_b128 v[176:179], v113 offset:20480
	ds_read_b128 v[180:183], v113 offset:22528
	s_waitcnt lgkmcnt(11)
	v_mfma_f32_16x16x32_bf16 v[92:95], v[130:133], v[114:117], v[92:95]
	s_waitcnt lgkmcnt(10)
	v_mfma_f32_16x16x32_bf16 v[88:91], v[134:137], v[114:117], v[88:91]
	s_waitcnt lgkmcnt(9)
	v_mfma_f32_16x16x32_bf16 v[84:87], v[138:141], v[114:117], v[84:87]
	s_waitcnt lgkmcnt(8)
	v_mfma_f32_16x16x32_bf16 v[76:79], v[142:145], v[114:117], v[76:79]
	v_mfma_f32_16x16x32_bf16 v[72:75], v[130:133], v[118:121], v[72:75]
	v_mfma_f32_16x16x32_bf16 v[68:71], v[134:137], v[118:121], v[68:71]
	v_mfma_f32_16x16x32_bf16 v[64:67], v[138:141], v[118:121], v[64:67]
	v_mfma_f32_16x16x32_bf16 v[60:63], v[142:145], v[118:121], v[60:63]
	v_mfma_f32_16x16x32_bf16 v[56:59], v[130:133], v[122:125], v[56:59]
	v_mfma_f32_16x16x32_bf16 v[52:55], v[134:137], v[122:125], v[52:55]
	v_mfma_f32_16x16x32_bf16 v[48:51], v[138:141], v[122:125], v[48:51]
	v_mfma_f32_16x16x32_bf16 v[44:47], v[142:145], v[122:125], v[44:47]
	v_mfma_f32_16x16x32_bf16 v[40:43], v[130:133], v[126:129], v[40:43]
	v_mfma_f32_16x16x32_bf16 v[36:39], v[134:137], v[126:129], v[36:39]
	v_mfma_f32_16x16x32_bf16 v[32:35], v[138:141], v[126:129], v[32:35]
	v_mfma_f32_16x16x32_bf16 v[80:83], v[142:145], v[126:129], v[80:83]
	s_waitcnt lgkmcnt(3)
	v_mfma_f32_16x16x32_bf16 v[92:95], v[168:171], v[146:149], v[92:95]
	s_addk_i32 s61, 0x80
	s_cmp_lg_u32 s30, 0x78000
	s_mov_b32 s62, s30
	s_waitcnt lgkmcnt(2)
	v_mfma_f32_16x16x32_bf16 v[88:91], v[172:175], v[146:149], v[88:91]
	s_waitcnt lgkmcnt(1)
	v_mfma_f32_16x16x32_bf16 v[84:87], v[176:179], v[146:149], v[84:87]
	s_waitcnt lgkmcnt(0)
	v_mfma_f32_16x16x32_bf16 v[76:79], v[180:183], v[146:149], v[76:79]
	v_mfma_f32_16x16x32_bf16 v[72:75], v[168:171], v[150:153], v[72:75]
	v_mfma_f32_16x16x32_bf16 v[68:71], v[172:175], v[150:153], v[68:71]
	v_mfma_f32_16x16x32_bf16 v[64:67], v[176:179], v[150:153], v[64:67]
	v_mfma_f32_16x16x32_bf16 v[60:63], v[180:183], v[150:153], v[60:63]
	v_mfma_f32_16x16x32_bf16 v[56:59], v[168:171], v[154:157], v[56:59]
	v_mfma_f32_16x16x32_bf16 v[52:55], v[172:175], v[154:157], v[52:55]
	v_mfma_f32_16x16x32_bf16 v[48:51], v[176:179], v[154:157], v[48:51]
	v_mfma_f32_16x16x32_bf16 v[44:47], v[180:183], v[154:157], v[44:47]
	v_mfma_f32_16x16x32_bf16 v[40:43], v[168:171], v[164:167], v[40:43]
	v_mfma_f32_16x16x32_bf16 v[36:39], v[172:175], v[164:167], v[36:39]
	v_mfma_f32_16x16x32_bf16 v[32:35], v[176:179], v[164:167], v[32:35]
	v_mfma_f32_16x16x32_bf16 v[80:83], v[180:183], v[164:167], v[80:83]
	s_cbranch_scc1 .LBB0_2236
	s_ashr_i32 s12, s57, 31
	s_add_u32 s13, s40, s57
	s_addc_u32 s12, s41, s12
	s_ashr_i32 s16, s56, 31
	s_add_u32 s17, s40, s56
	s_addc_u32 s16, s41, s16
	s_add_u32 s13, s13, s20
	s_addc_u32 s18, s12, s21
	s_add_u32 s12, s13, s22
	s_addc_u32 s13, s18, s23
	s_add_u32 s8, s17, s8
	s_addc_u32 s9, s16, s9
	s_add_u32 s8, s8, s58
	s_addc_u32 s9, s9, 0
	v_mul_lo_u32 v102, v102, s54
	s_add_u32 s16, s8, 0x1e20000
	s_addc_u32 s17, s9, 0
	s_and_b32 s13, s13, 0xffff
	v_or_b32_e32 v102, v98, v102
	v_readfirstlane_b32 s20, v96
	v_mul_lo_u32 v103, v103, s54
	v_mul_lo_u32 v104, v105, s54
	v_mul_lo_u32 v105, v107, s54
	s_mov_b32 s8, s12
	s_mov_b32 s9, s13
	v_lshlrev_b32_e32 v102, 1, v102
	s_mov_b32 m0, s20
	v_readfirstlane_b32 s20, v97
	v_or_b32_e32 v103, v98, v103
	v_or_b32_e32 v104, v98, v104
	v_or_b32_e32 v98, v98, v105
	s_and_b32 s17, s17, 0xffff
	s_mov_b32 s18, s10
	s_mov_b32 s19, s11
	v_add_u32_e32 v105, 0x4000, v99
	s_waitcnt vmcnt(0)
	s_waitcnt vmcnt(0)
	s_barrier
	buffer_load_dwordx4 v102, s[8:11], 0 offen lds
	s_mov_b32 m0, s20
	v_readfirstlane_b32 s20, v99
	v_lshlrev_b32_e32 v103, 1, v103
	buffer_load_dwordx4 v102, s[16:19], 0 offen lds
	s_mov_b32 m0, s20
	v_readfirstlane_b32 s20, v105
	v_add_u32_e32 v106, 0x4000, v100
	buffer_load_dwordx4 v103, s[8:11], 0 offen lds
	s_mov_b32 m0, s20
	v_readfirstlane_b32 s20, v100
	v_lshlrev_b32_e32 v104, 1, v104
	buffer_load_dwordx4 v103, s[16:19], 0 offen lds
	s_mov_b32 m0, s20
	v_readfirstlane_b32 s20, v106
	buffer_load_dwordx4 v104, s[8:11], 0 offen lds
	s_mov_b32 m0, s20
	v_readfirstlane_b32 s20, v101
	v_lshlrev_b32_e32 v98, 1, v98
	v_add_u32_e32 v107, 0x4000, v101
	buffer_load_dwordx4 v104, s[16:19], 0 offen lds
	s_mov_b32 m0, s20
	v_add3_u32 v96, v112, s60, v111
	buffer_load_dwordx4 v98, s[8:11], 0 offen lds
	v_readfirstlane_b32 s8, v107
	s_mov_b32 m0, s8
	v_add3_u32 v108, v109, s60, v111
	buffer_load_dwordx4 v98, s[16:19], 0 offen lds
	ds_read_b128 v[100:103], v96 offset:55296
	ds_read_b128 v[104:107], v96 offset:53248
	ds_read_b128 v[114:117], v96 offset:51200
	ds_read_b128 v[118:121], v96 offset:49152
	v_add3_u32 v96, v112, s59, v111
	v_add3_u32 v112, v109, s59, v111
	ds_read_b128 v[122:125], v96 offset:38912
	ds_read_b128 v[126:129], v96 offset:36864
	ds_read_b128 v[130:133], v96 offset:34816
	ds_read_b128 v[134:137], v96 offset:32768
	ds_read_b128 v[96:99], v108 offset:55296
	ds_read_b128 v[138:141], v108 offset:53248
	ds_read_b128 v[142:145], v108 offset:51200
	ds_read_b128 v[146:149], v108 offset:49152
	ds_read_b128 v[108:111], v112 offset:38912
	ds_read_b128 v[150:153], v112 offset:36864
	ds_read_b128 v[154:157], v112 offset:34816
	ds_read_b128 v[164:167], v112 offset:32768
	s_waitcnt lgkmcnt(0)
	v_mfma_f32_16x16x32_bf16 v[88:91], v[142:145], v[164:167], v[88:91]
	v_mfma_f32_16x16x32_bf16 v[84:87], v[138:141], v[164:167], v[84:87]
	v_mfma_f32_16x16x32_bf16 v[76:79], v[96:99], v[164:167], v[76:79]
	v_mfma_f32_16x16x32_bf16 v[72:75], v[146:149], v[154:157], v[72:75]
	v_mfma_f32_16x16x32_bf16 v[68:71], v[142:145], v[154:157], v[68:71]
	v_mfma_f32_16x16x32_bf16 v[64:67], v[138:141], v[154:157], v[64:67]
	v_mfma_f32_16x16x32_bf16 v[60:63], v[96:99], v[154:157], v[60:63]
	v_mfma_f32_16x16x32_bf16 v[56:59], v[146:149], v[150:153], v[56:59]
	v_mfma_f32_16x16x32_bf16 v[52:55], v[142:145], v[150:153], v[52:55]
	v_mfma_f32_16x16x32_bf16 v[48:51], v[138:141], v[150:153], v[48:51]
	v_mfma_f32_16x16x32_bf16 v[44:47], v[96:99], v[150:153], v[44:47]
	v_mfma_f32_16x16x32_bf16 v[40:43], v[146:149], v[108:111], v[40:43]
	v_mfma_f32_16x16x32_bf16 v[36:39], v[142:145], v[108:111], v[36:39]
	v_mfma_f32_16x16x32_bf16 v[32:35], v[138:141], v[108:111], v[32:35]
	v_mfma_f32_16x16x32_bf16 v[92:95], v[146:149], v[164:167], v[92:95]
	v_mfma_f32_16x16x32_bf16 v[108:111], v[96:99], v[108:111], v[80:83]
	v_mfma_f32_16x16x32_bf16 v[96:99], v[118:121], v[134:137], v[92:95]
	s_mov_b64 s[18:19], -1
	s_cmp_eq_u32 s53, 2
	v_mfma_f32_16x16x32_bf16 v[88:91], v[114:117], v[134:137], v[88:91]
	v_mfma_f32_16x16x32_bf16 v[84:87], v[104:107], v[134:137], v[84:87]
	v_mfma_f32_16x16x32_bf16 v[80:83], v[100:103], v[134:137], v[76:79]
	v_mfma_f32_16x16x32_bf16 v[76:79], v[118:121], v[130:133], v[72:75]
	v_mfma_f32_16x16x32_bf16 v[72:75], v[114:117], v[130:133], v[68:71]
	v_mfma_f32_16x16x32_bf16 v[68:71], v[104:107], v[130:133], v[64:67]
	v_mfma_f32_16x16x32_bf16 v[64:67], v[100:103], v[130:133], v[60:63]
	v_mfma_f32_16x16x32_bf16 v[60:63], v[118:121], v[126:129], v[56:59]
	v_mfma_f32_16x16x32_bf16 v[56:59], v[114:117], v[126:129], v[52:55]
	v_mfma_f32_16x16x32_bf16 v[52:55], v[104:107], v[126:129], v[48:51]
	v_mfma_f32_16x16x32_bf16 v[48:51], v[100:103], v[126:129], v[44:47]
	v_mfma_f32_16x16x32_bf16 v[44:47], v[118:121], v[122:125], v[40:43]
	v_mfma_f32_16x16x32_bf16 v[40:43], v[114:117], v[122:125], v[36:39]
	v_mfma_f32_16x16x32_bf16 v[36:39], v[104:107], v[122:125], v[32:35]
	v_mfma_f32_16x16x32_bf16 v[32:35], v[100:103], v[122:125], v[108:111]
	s_cbranch_scc1 .LBB0_2239
	s_mov_b32 s8, 0
	s_ashr_i32 s18, s8, 31
	s_add_u32 s8, s40, s8
	s_mov_b32 s9, 0
	s_addc_u32 s18, s41, s18
	s_ashr_i32 s19, s9, 31
	s_add_u32 s20, s40, s9
	s_addc_u32 s19, s41, s19
	s_add_u32 s8, s8, s34
	s_addc_u32 s9, s18, s35
	s_add_u32 s8, s8, 0x3cb8000
	s_addc_u32 s9, s9, 0
	s_add_i32 s18, s52, s55
	s_add_u32 s18, s20, s18
	s_addc_u32 s19, s19, 0
	s_add_u32 s20, s18, 0x2120000
	s_addc_u32 s21, s19, 0
	s_mov_b64 s[18:19], 0

.LBB0_2244:
	s_and_b32 s58, s54, 0x8000
	v_readfirstlane_b32 s98, v166
	s_waitcnt vmcnt(0)
	s_waitcnt vmcnt(0)
	s_add_u32 s99, s98, s58
	s_add_u32 m0, s99, 0x0
	s_barrier
	buffer_load_dwordx4 v171, s[12:15], s57 offen lds
	s_add_u32 m0, s99, 0x4000
	s_mov_b32 s18, s14
	s_mov_b32 s19, s15
	buffer_load_dwordx4 v171, s[16:19], s57 offen lds
	s_add_u32 m0, s99, 0x1000
	s_nop 0
	buffer_load_dwordx4 v172, s[12:15], s57 offen lds
	s_add_u32 m0, s99, 0x5000
	s_nop 0
	buffer_load_dwordx4 v172, s[16:19], s57 offen lds
	s_add_u32 m0, s99, 0x2000
	s_nop 0
	buffer_load_dwordx4 v173, s[12:15], s57 offen lds
	s_add_u32 m0, s99, 0x6000
	s_nop 0
	buffer_load_dwordx4 v173, s[16:19], s57 offen lds
	s_add_u32 m0, s99, 0x3000
	s_nop 0
	buffer_load_dwordx4 v174, s[12:15], s57 offen lds
	s_add_u32 m0, s99, 0x7000
	s_nop 0
	buffer_load_dwordx4 v174, s[16:19], s57 offen lds
	s_add_i32 s18, s54, 0xffff8000
	s_and_b32 s18, s18, 0x8000
	v_or_b32_e32 v175, s18, v164
	v_add3_u32 v188, v175, s56, v160
	v_add3_u32 v175, v175, s55, v160
	ds_read_b128 v[176:179], v188
	ds_read_b128 v[180:183], v188 offset:2048
	ds_read_b128 v[184:187], v188 offset:4096
	ds_read_b128 v[188:191], v188 offset:6144
	ds_read_b128 v[196:199], v175 offset:16384
	ds_read_b128 v[200:203], v175 offset:18432
	ds_read_b128 v[204:207], v175 offset:20480
	ds_read_b128 v[208:211], v175 offset:22528
	v_or_b32_e32 v175, s18, v163
	v_add3_u32 v224, v175, s56, v160
	v_add3_u32 v175, v175, s55, v160
	ds_read_b128 v[212:215], v224
	ds_read_b128 v[216:219], v224 offset:2048
	ds_read_b128 v[220:223], v224 offset:4096
	ds_read_b128 v[224:227], v224 offset:6144
	ds_read_b128 v[228:231], v175 offset:16384
	ds_read_b128 v[232:235], v175 offset:18432
	ds_read_b128 v[236:239], v175 offset:20480
	ds_read_b128 v[240:243], v175 offset:22528
	s_waitcnt lgkmcnt(11)
	v_mfma_f32_16x16x32_bf16 v[156:159], v[196:199], v[176:179], v[156:159]
	s_waitcnt lgkmcnt(10)
	v_mfma_f32_16x16x32_bf16 v[152:155], v[200:203], v[176:179], v[152:155]
	s_waitcnt lgkmcnt(9)
	v_mfma_f32_16x16x32_bf16 v[148:151], v[204:207], v[176:179], v[148:151]
	s_waitcnt lgkmcnt(8)
	v_mfma_f32_16x16x32_bf16 v[140:143], v[208:211], v[176:179], v[140:143]
	v_mfma_f32_16x16x32_bf16 v[136:139], v[196:199], v[180:183], v[136:139]
	v_mfma_f32_16x16x32_bf16 v[132:135], v[200:203], v[180:183], v[132:135]
	v_mfma_f32_16x16x32_bf16 v[128:131], v[204:207], v[180:183], v[128:131]
	v_mfma_f32_16x16x32_bf16 v[124:127], v[208:211], v[180:183], v[124:127]
	v_mfma_f32_16x16x32_bf16 v[120:123], v[196:199], v[184:187], v[120:123]
	v_mfma_f32_16x16x32_bf16 v[116:119], v[200:203], v[184:187], v[116:119]
	v_mfma_f32_16x16x32_bf16 v[112:115], v[204:207], v[184:187], v[112:115]
	v_mfma_f32_16x16x32_bf16 v[108:111], v[208:211], v[184:187], v[108:111]
	v_mfma_f32_16x16x32_bf16 v[104:107], v[196:199], v[188:191], v[104:107]
	v_mfma_f32_16x16x32_bf16 v[100:103], v[200:203], v[188:191], v[100:103]
	v_mfma_f32_16x16x32_bf16 v[92:95], v[204:207], v[188:191], v[92:95]
	v_mfma_f32_16x16x32_bf16 v[144:147], v[208:211], v[188:191], v[144:147]
	s_waitcnt lgkmcnt(3)
	v_mfma_f32_16x16x32_bf16 v[156:159], v[228:231], v[212:215], v[156:159]
	s_add_i32 s54, s54, 0x8000
	s_addk_i32 s57, 0x80
	s_cmp_eq_u32 s23, s54
	s_waitcnt lgkmcnt(2)
	v_mfma_f32_16x16x32_bf16 v[152:155], v[232:235], v[212:215], v[152:155]
	s_waitcnt lgkmcnt(1)
	v_mfma_f32_16x16x32_bf16 v[148:151], v[236:239], v[212:215], v[148:151]
	s_waitcnt lgkmcnt(0)
	v_mfma_f32_16x16x32_bf16 v[140:143], v[240:243], v[212:215], v[140:143]
	v_mfma_f32_16x16x32_bf16 v[136:139], v[228:231], v[216:219], v[136:139]
	v_mfma_f32_16x16x32_bf16 v[132:135], v[232:235], v[216:219], v[132:135]
	v_mfma_f32_16x16x32_bf16 v[128:131], v[236:239], v[216:219], v[128:131]
	v_mfma_f32_16x16x32_bf16 v[124:127], v[240:243], v[216:219], v[124:127]
	v_mfma_f32_16x16x32_bf16 v[120:123], v[228:231], v[220:223], v[120:123]
	v_mfma_f32_16x16x32_bf16 v[116:119], v[232:235], v[220:223], v[116:119]
	v_mfma_f32_16x16x32_bf16 v[112:115], v[236:239], v[220:223], v[112:115]
	v_mfma_f32_16x16x32_bf16 v[108:111], v[240:243], v[220:223], v[108:111]
	v_mfma_f32_16x16x32_bf16 v[104:107], v[228:231], v[224:227], v[104:107]
	v_mfma_f32_16x16x32_bf16 v[100:103], v[232:235], v[224:227], v[100:103]
	v_mfma_f32_16x16x32_bf16 v[92:95], v[236:239], v[224:227], v[92:95]
	v_mfma_f32_16x16x32_bf16 v[144:147], v[240:243], v[224:227], v[144:147]
	s_cbranch_scc0 .LBB0_2244
	s_cmp_eq_u64 s[8:9], 0
	s_waitcnt vmcnt(0)
	s_cselect_b64 s[12:13], -1, 0
	s_and_b64 vcc, exec, s[12:13]
	s_waitcnt vmcnt(0)
	s_barrier
	s_cbranch_vccnz .LBB0_2221
	v_mul_lo_u32 v167, v167, s22
	v_mul_lo_u32 v168, v168, s22
	v_mul_lo_u32 v169, v169, s22
	v_mul_lo_u32 v170, v170, s22
	v_or_b32_e32 v170, v165, v170
	v_or_b32_e32 v169, v165, v169
	v_or_b32_e32 v168, v165, v168
	v_or_b32_e32 v165, v165, v167
	v_add_u32_e32 v176, 0x4000, v166
	v_readfirstlane_b32 s16, v166
	v_add_u32_e32 v173, 0x1000, v166
	s_and_b32 s9, s9, 0xffff
	v_lshlrev_b32_e32 v165, 1, v165
	s_mov_b32 m0, s16
	v_readfirstlane_b32 s16, v176
	v_add_u32_e32 v175, 0x5000, v166
	s_and_b32 s21, s21, 0xffff
	s_mov_b32 s22, s10
	s_mov_b32 s23, s11
	buffer_load_dwordx4 v165, s[8:11], 0 offen lds
	s_mov_b32 m0, s16
	v_readfirstlane_b32 s16, v173
	v_add_u32_e32 v172, 0x2000, v166
	v_lshlrev_b32_e32 v168, 1, v168
	buffer_load_dwordx4 v165, s[20:23], 0 offen lds
	s_mov_b32 m0, s16
	v_readfirstlane_b32 s16, v175
	v_add_u32_e32 v174, 0x6000, v166
	buffer_load_dwordx4 v168, s[8:11], 0 offen lds
	s_mov_b32 m0, s16
	v_readfirstlane_b32 s16, v172
	v_add_u32_e32 v171, 0x3000, v166
	v_lshlrev_b32_e32 v169, 1, v169
	buffer_load_dwordx4 v168, s[20:23], 0 offen lds
	s_mov_b32 m0, s16
	v_readfirstlane_b32 s16, v174
	buffer_load_dwordx4 v169, s[8:11], 0 offen lds
	s_mov_b32 m0, s16
	v_readfirstlane_b32 s16, v171
	v_add_u32_e32 v167, 0x7000, v166
	v_lshlrev_b32_e32 v170, 1, v170
	buffer_load_dwordx4 v169, s[20:23], 0 offen lds
	s_mov_b32 m0, s16
	s_nop 0
	buffer_load_dwordx4 v170, s[8:11], 0 offen lds
	v_readfirstlane_b32 s8, v167
	s_mov_b32 m0, s8
	s_nop 0
	buffer_load_dwordx4 v170, s[20:23], 0 offen lds
	s_branch .LBB0_2221

.LBB0_2310:
	s_add_i32 s30, s50, 0x8000
	s_and_b32 s51, s30, 0x8000
	v_readfirstlane_b32 s98, v68
	v_readfirstlane_b32 s99, v70
	v_readfirstlane_b32 s100, v71
	v_readfirstlane_b32 s101, v72
	s_waitcnt vmcnt(0)
	s_nop 0
	s_add_u32 m0, s98, s51
	s_barrier
	buffer_load_dwordx4 v67, s[12:15], s49 offen lds
	s_add_u32 m0, s98, s51
	s_add_u32 m0, m0, 0x4000
	s_nop 0
	buffer_load_dwordx4 v67, s[16:19], s49 offen lds
	s_add_u32 m0, s99, s51
	s_nop 0
	buffer_load_dwordx4 v66, s[12:15], s49 offen lds
	s_add_u32 m0, s99, s51
	s_add_u32 m0, m0, 0x4000
	s_nop 0
	buffer_load_dwordx4 v66, s[16:19], s49 offen lds
	s_add_u32 m0, s100, s51
	s_nop 0
	buffer_load_dwordx4 v65, s[12:15], s49 offen lds
	s_add_u32 m0, s100, s51
	s_add_u32 m0, m0, 0x4000
	s_nop 0
	buffer_load_dwordx4 v65, s[16:19], s49 offen lds
	s_add_u32 m0, s101, s51
	s_nop 0
	buffer_load_dwordx4 v64, s[12:15], s49 offen lds
	s_add_u32 m0, s101, s51
	s_add_u32 m0, m0, 0x4000
	s_and_b32 s31, s50, 0x8000
	buffer_load_dwordx4 v64, s[16:19], s49 offen lds
	v_or_b32_e32 v80, s31, v75
	v_add3_u32 v83, v80, s48, v73
	v_add3_u32 v80, v80, s27, v73
	ds_read_b128 v[76:79], v83
	ds_read_b128 v[84:87], v83 offset:2048
	ds_read_b128 v[88:91], v83 offset:4096
	ds_read_b128 v[92:95], v83 offset:6144
	ds_read_b128 v[96:99], v80 offset:16384
	ds_read_b128 v[100:103], v80 offset:18432
	ds_read_b128 v[104:107], v80 offset:20480
	ds_read_b128 v[108:111], v80 offset:22528
	v_or_b32_e32 v80, s31, v74
	v_add3_u32 v83, v80, s48, v73
	v_add3_u32 v80, v80, s27, v73
	ds_read_b128 v[112:115], v83
	ds_read_b128 v[116:119], v83 offset:2048
	ds_read_b128 v[120:123], v83 offset:4096
	ds_read_b128 v[124:127], v83 offset:6144
	ds_read_b128 v[128:131], v80 offset:16384
	ds_read_b128 v[132:135], v80 offset:18432
	ds_read_b128 v[136:139], v80 offset:20480
	ds_read_b128 v[140:143], v80 offset:22528
	s_waitcnt lgkmcnt(11)
	v_mfma_f32_16x16x32_bf16 v[60:63], v[96:99], v[76:79], v[60:63]
	s_waitcnt lgkmcnt(10)
	v_mfma_f32_16x16x32_bf16 v[56:59], v[100:103], v[76:79], v[56:59]
	s_waitcnt lgkmcnt(9)
	v_mfma_f32_16x16x32_bf16 v[52:55], v[104:107], v[76:79], v[52:55]
	s_waitcnt lgkmcnt(8)
	v_mfma_f32_16x16x32_bf16 v[48:51], v[108:111], v[76:79], v[48:51]
	v_mfma_f32_16x16x32_bf16 v[44:47], v[96:99], v[84:87], v[44:47]
	v_mfma_f32_16x16x32_bf16 v[36:39], v[100:103], v[84:87], v[36:39]
	v_mfma_f32_16x16x32_bf16 v[32:35], v[104:107], v[84:87], v[32:35]
	v_mfma_f32_16x16x32_bf16 v[28:31], v[108:111], v[84:87], v[28:31]
	v_mfma_f32_16x16x32_bf16 v[24:27], v[96:99], v[88:91], v[24:27]
	v_mfma_f32_16x16x32_bf16 v[20:23], v[100:103], v[88:91], v[20:23]
	v_mfma_f32_16x16x32_bf16 v[16:19], v[104:107], v[88:91], v[16:19]
	v_mfma_f32_16x16x32_bf16 v[12:15], v[108:111], v[88:91], v[12:15]
	v_mfma_f32_16x16x32_bf16 v[8:11], v[96:99], v[92:95], v[8:11]
	v_mfma_f32_16x16x32_bf16 v[4:7], v[100:103], v[92:95], v[4:7]
	v_mfma_f32_16x16x32_bf16 v[0:3], v[104:107], v[92:95], v[0:3]
	v_mfma_f32_16x16x32_bf16 v[40:43], v[108:111], v[92:95], v[40:43]
	s_waitcnt lgkmcnt(3)
	v_mfma_f32_16x16x32_bf16 v[60:63], v[128:131], v[112:115], v[60:63]
	s_addk_i32 s49, 0x80
	s_cmpk_eq_i32 s49, 0x800
	s_mov_b32 s50, s30
	s_waitcnt lgkmcnt(2)
	v_mfma_f32_16x16x32_bf16 v[56:59], v[132:135], v[112:115], v[56:59]
	s_waitcnt lgkmcnt(1)
	v_mfma_f32_16x16x32_bf16 v[52:55], v[136:139], v[112:115], v[52:55]
	s_waitcnt lgkmcnt(0)
	v_mfma_f32_16x16x32_bf16 v[48:51], v[140:143], v[112:115], v[48:51]
	v_mfma_f32_16x16x32_bf16 v[44:47], v[128:131], v[116:119], v[44:47]
	v_mfma_f32_16x16x32_bf16 v[36:39], v[132:135], v[116:119], v[36:39]
	v_mfma_f32_16x16x32_bf16 v[32:35], v[136:139], v[116:119], v[32:35]
	v_mfma_f32_16x16x32_bf16 v[28:31], v[140:143], v[116:119], v[28:31]
	v_mfma_f32_16x16x32_bf16 v[24:27], v[128:131], v[120:123], v[24:27]
	v_mfma_f32_16x16x32_bf16 v[20:23], v[132:135], v[120:123], v[20:23]
	v_mfma_f32_16x16x32_bf16 v[16:19], v[136:139], v[120:123], v[16:19]
	v_mfma_f32_16x16x32_bf16 v[12:15], v[140:143], v[120:123], v[12:15]
	v_mfma_f32_16x16x32_bf16 v[8:11], v[128:131], v[124:127], v[8:11]
	v_mfma_f32_16x16x32_bf16 v[4:7], v[132:135], v[124:127], v[4:7]
	v_mfma_f32_16x16x32_bf16 v[0:3], v[136:139], v[124:127], v[0:3]
	v_mfma_f32_16x16x32_bf16 v[40:43], v[140:143], v[124:127], v[40:43]
	s_cbranch_scc0 .LBB0_2310
	s_waitcnt vmcnt(0)
	s_andn2_b64 vcc, exec, s[28:29]
	s_waitcnt vmcnt(0)
	s_barrier
	s_cbranch_vccnz .LBB0_2313
	s_lshl_b64 s[12:13], s[34:35], 1
	s_add_u32 s12, s6, s12
	s_addc_u32 s6, s45, s13
	s_lshl_b32 s13, s36, 1
	s_add_u32 s16, s46, s13
	s_addc_u32 s17, s47, 0
	s_and_b32 s13, s6, 0xffff
	v_readfirstlane_b32 s6, v68
	s_mov_b32 m0, s6
	v_readfirstlane_b32 s6, v69
	v_add_u32_e32 v78, 0x4000, v70
	s_and_b32 s17, s17, 0xffff
	s_mov_b32 s18, s14
	s_mov_b32 s19, s15
	buffer_load_dwordx4 v67, s[12:15], 0 offen lds
	s_mov_b32 m0, s6
	v_readfirstlane_b32 s6, v70
	buffer_load_dwordx4 v67, s[16:19], 0 offen lds
	s_mov_b32 m0, s6
	v_readfirstlane_b32 s6, v78
	v_add_u32_e32 v77, 0x4000, v71
	buffer_load_dwordx4 v66, s[12:15], 0 offen lds
	s_mov_b32 m0, s6
	v_readfirstlane_b32 s6, v71
	buffer_load_dwordx4 v66, s[16:19], 0 offen lds
	s_mov_b32 m0, s6
	v_readfirstlane_b32 s6, v77
	v_add_u32_e32 v76, 0x4000, v72
	buffer_load_dwordx4 v65, s[12:15], 0 offen lds
	s_mov_b32 m0, s6
	v_readfirstlane_b32 s6, v72
	buffer_load_dwordx4 v65, s[16:19], 0 offen lds
	s_mov_b32 m0, s6
	v_readfirstlane_b32 s6, v76
	buffer_load_dwordx4 v64, s[12:15], 0 offen lds
	s_mov_b32 m0, s6
	s_nop 0
	buffer_load_dwordx4 v64, s[16:19], 0 offen lds

.LBB0_2506:
	s_add_i32 s30, s54, 0x8000
	s_and_b32 s55, s30, 0x8000
	v_readfirstlane_b32 s98, v68
	v_readfirstlane_b32 s99, v70
	v_readfirstlane_b32 s100, v71
	v_readfirstlane_b32 s101, v72
	s_waitcnt vmcnt(0)
	s_nop 0
	s_add_u32 m0, s98, s55
	s_barrier
	buffer_load_dwordx4 v67, s[12:15], s53 offen lds
	s_add_u32 m0, s98, s55
	s_add_u32 m0, m0, 0x4000
	s_nop 0
	buffer_load_dwordx4 v67, s[16:19], s53 offen lds
	s_add_u32 m0, s99, s55
	s_nop 0
	buffer_load_dwordx4 v66, s[12:15], s53 offen lds
	s_add_u32 m0, s99, s55
	s_add_u32 m0, m0, 0x4000
	s_nop 0
	buffer_load_dwordx4 v66, s[16:19], s53 offen lds
	s_add_u32 m0, s100, s55
	s_nop 0
	buffer_load_dwordx4 v65, s[12:15], s53 offen lds
	s_add_u32 m0, s100, s55
	s_add_u32 m0, m0, 0x4000
	s_nop 0
	buffer_load_dwordx4 v65, s[16:19], s53 offen lds
	s_add_u32 m0, s101, s55
	s_nop 0
	buffer_load_dwordx4 v64, s[12:15], s53 offen lds
	s_add_u32 m0, s101, s55
	s_add_u32 m0, m0, 0x4000
	s_and_b32 s31, s54, 0x8000
	buffer_load_dwordx4 v64, s[16:19], s53 offen lds
	v_or_b32_e32 v80, s31, v75
	v_add3_u32 v83, v80, s52, v73
	v_add3_u32 v80, v80, s29, v73
	ds_read_b128 v[76:79], v83
	ds_read_b128 v[84:87], v83 offset:2048
	ds_read_b128 v[88:91], v83 offset:4096
	ds_read_b128 v[92:95], v83 offset:6144
	ds_read_b128 v[96:99], v80 offset:16384
	ds_read_b128 v[100:103], v80 offset:18432
	ds_read_b128 v[104:107], v80 offset:20480
	ds_read_b128 v[108:111], v80 offset:22528
	v_or_b32_e32 v80, s31, v74
	v_add3_u32 v83, v80, s52, v73
	v_add3_u32 v80, v80, s29, v73
	ds_read_b128 v[112:115], v83
	ds_read_b128 v[116:119], v83 offset:2048
	ds_read_b128 v[120:123], v83 offset:4096
	ds_read_b128 v[124:127], v83 offset:6144
	ds_read_b128 v[128:131], v80 offset:16384
	ds_read_b128 v[132:135], v80 offset:18432
	ds_read_b128 v[136:139], v80 offset:20480
	ds_read_b128 v[140:143], v80 offset:22528
	s_waitcnt lgkmcnt(11)
	v_mfma_f32_16x16x32_bf16 v[60:63], v[96:99], v[76:79], v[60:63]
	s_waitcnt lgkmcnt(10)
	v_mfma_f32_16x16x32_bf16 v[56:59], v[100:103], v[76:79], v[56:59]
	s_waitcnt lgkmcnt(9)
	v_mfma_f32_16x16x32_bf16 v[52:55], v[104:107], v[76:79], v[52:55]
	s_waitcnt lgkmcnt(8)
	v_mfma_f32_16x16x32_bf16 v[48:51], v[108:111], v[76:79], v[48:51]
	v_mfma_f32_16x16x32_bf16 v[44:47], v[96:99], v[84:87], v[44:47]
	v_mfma_f32_16x16x32_bf16 v[36:39], v[100:103], v[84:87], v[36:39]
	v_mfma_f32_16x16x32_bf16 v[32:35], v[104:107], v[84:87], v[32:35]
	v_mfma_f32_16x16x32_bf16 v[28:31], v[108:111], v[84:87], v[28:31]
	v_mfma_f32_16x16x32_bf16 v[24:27], v[96:99], v[88:91], v[24:27]
	v_mfma_f32_16x16x32_bf16 v[20:23], v[100:103], v[88:91], v[20:23]
	v_mfma_f32_16x16x32_bf16 v[16:19], v[104:107], v[88:91], v[16:19]
	v_mfma_f32_16x16x32_bf16 v[12:15], v[108:111], v[88:91], v[12:15]
	v_mfma_f32_16x16x32_bf16 v[8:11], v[96:99], v[92:95], v[8:11]
	v_mfma_f32_16x16x32_bf16 v[4:7], v[100:103], v[92:95], v[4:7]
	v_mfma_f32_16x16x32_bf16 v[0:3], v[104:107], v[92:95], v[0:3]
	v_mfma_f32_16x16x32_bf16 v[40:43], v[108:111], v[92:95], v[40:43]
	s_waitcnt lgkmcnt(3)
	v_mfma_f32_16x16x32_bf16 v[60:63], v[128:131], v[112:115], v[60:63]
	s_addk_i32 s53, 0x80
	s_cmpk_eq_i32 s53, 0x2000
	s_mov_b32 s54, s30
	s_waitcnt lgkmcnt(2)
	v_mfma_f32_16x16x32_bf16 v[56:59], v[132:135], v[112:115], v[56:59]
	s_waitcnt lgkmcnt(1)
	v_mfma_f32_16x16x32_bf16 v[52:55], v[136:139], v[112:115], v[52:55]
	s_waitcnt lgkmcnt(0)
	v_mfma_f32_16x16x32_bf16 v[48:51], v[140:143], v[112:115], v[48:51]
	v_mfma_f32_16x16x32_bf16 v[44:47], v[128:131], v[116:119], v[44:47]
	v_mfma_f32_16x16x32_bf16 v[36:39], v[132:135], v[116:119], v[36:39]
	v_mfma_f32_16x16x32_bf16 v[32:35], v[136:139], v[116:119], v[32:35]
	v_mfma_f32_16x16x32_bf16 v[28:31], v[140:143], v[116:119], v[28:31]
	v_mfma_f32_16x16x32_bf16 v[24:27], v[128:131], v[120:123], v[24:27]
	v_mfma_f32_16x16x32_bf16 v[20:23], v[132:135], v[120:123], v[20:23]
	v_mfma_f32_16x16x32_bf16 v[16:19], v[136:139], v[120:123], v[16:19]
	v_mfma_f32_16x16x32_bf16 v[12:15], v[140:143], v[120:123], v[12:15]
	v_mfma_f32_16x16x32_bf16 v[8:11], v[128:131], v[124:127], v[8:11]
	v_mfma_f32_16x16x32_bf16 v[4:7], v[132:135], v[124:127], v[4:7]
	v_mfma_f32_16x16x32_bf16 v[0:3], v[136:139], v[124:127], v[0:3]
	v_mfma_f32_16x16x32_bf16 v[40:43], v[140:143], v[124:127], v[40:43]
	s_cbranch_scc0 .LBB0_2506
	s_waitcnt vmcnt(0)
	s_andn2_b64 vcc, exec, s[34:35]
	s_waitcnt vmcnt(0)
	s_barrier
	s_cbranch_vccnz .LBB0_2509
	s_lshl_b64 s[12:13], s[36:37], 1
	s_add_u32 s12, s48, s12
	s_addc_u32 s13, s49, s13
	s_lshl_b32 s16, s38, 1
	s_add_u32 s16, s50, s16
	v_readfirstlane_b32 s30, v68
	s_addc_u32 s17, s51, 0
	s_and_b32 s13, s13, 0xffff
	s_mov_b32 m0, s30
	v_readfirstlane_b32 s30, v69
	v_add_u32_e32 v78, 0x4000, v70
	s_and_b32 s17, s17, 0xffff
	s_mov_b32 s18, s14
	s_mov_b32 s19, s15
	buffer_load_dwordx4 v67, s[12:15], 0 offen lds
	s_mov_b32 m0, s30
	v_readfirstlane_b32 s30, v70
	buffer_load_dwordx4 v67, s[16:19], 0 offen lds
	s_mov_b32 m0, s30
	v_readfirstlane_b32 s30, v78
	v_add_u32_e32 v77, 0x4000, v71
	buffer_load_dwordx4 v66, s[12:15], 0 offen lds
	s_mov_b32 m0, s30
	v_readfirstlane_b32 s30, v71
	buffer_load_dwordx4 v66, s[16:19], 0 offen lds
	s_mov_b32 m0, s30
	v_readfirstlane_b32 s30, v77
	buffer_load_dwordx4 v65, s[12:15], 0 offen lds
	s_mov_b32 m0, s30
	v_readfirstlane_b32 s30, v72
	v_add_u32_e32 v76, 0x4000, v72
	buffer_load_dwordx4 v65, s[16:19], 0 offen lds
	s_mov_b32 m0, s30
	s_nop 0
	buffer_load_dwordx4 v64, s[12:15], 0 offen lds
	v_readfirstlane_b32 s12, v76
	s_mov_b32 m0, s12
	s_nop 0
	buffer_load_dwordx4 v64, s[16:19], 0 offen lds
